# hand-written RWKV scan task (16-step chunks, all-f32 LDS staging, reduce-scatter readout) + prep staging loops de-serialised
# speedup vs baseline: 1.0215x; 1.0215x over previous
; DI void prep_phase(const Params& p, int l, char* smem, const bool dry = false) {
;     ...
;     for (int c = tid; c < DSH; c += 256) {
;       float pv;
;       if (t0.t == 0) pv = t0.isP ? 0.f : p.state_shift[(size_t)(l * 32 + t0.b) * DSH + c];
;       else pv = p.bnd[(size_t)(task - 1) * DSH + c];
;       rows[c] = pv;
;     }
.LBB0_1160:
.LBB0_1161:
	v_mov_b32_e32 v46, 0
	v_mov_b32_e32 v47, 0
	v_mov_b32_e32 v48, 0
	v_mov_b32_e32 v49, 0
	v_mov_b32_e32 v50, 0
	v_mov_b32_e32 v51, 0
	v_mov_b32_e32 v52, 0
	s_andn2_b64 vcc, exec, s[18:19]
	s_cbranch_vccnz .Lprep_bnd_nold
	s_mov_b64 s[22:23], 0x1000
	v_lshl_add_u64 v[54:55], v[38:39], 0, s[22:23]
	global_load_dword v46, v[38:39], off
	global_load_dword v47, v[38:39], off offset:1024
	global_load_dword v48, v[38:39], off offset:2048
	global_load_dword v49, v[38:39], off offset:3072
	global_load_dword v50, v[54:55], off
	global_load_dword v51, v[54:55], off offset:1024
	v_cmp_gt_i32_e32 vcc, 0x80, v4
	s_and_saveexec_b64 s[20:21], vcc
	global_load_dword v52, v[54:55], off offset:2048
	s_mov_b64 exec, s[20:21]
.Lprep_bnd_nold:
	s_waitcnt vmcnt(0)
	ds_write_b32 v40, v46
	ds_write_b32 v40, v47 offset:1024
	ds_write_b32 v40, v48 offset:2048
	ds_write_b32 v40, v49 offset:3072
	ds_write_b32 v40, v50 offset:4096
	ds_write_b32 v40, v51 offset:5120
	v_cmp_gt_i32_e32 vcc, 0x80, v4
	s_and_saveexec_b64 s[20:21], vcc
	ds_write_b32 v40, v52 offset:6144
	s_mov_b64 exec, s[20:21]

; DI void prep_phase(const Params& p, int l, char* smem, const bool dry = false) {
;     ...
;       for (int f = tid; f < 8 * 416; f += 256) {
;         int tk = f / 416, c4 = f - tk * 416;
;         *(float4*)(rows + (tk + 1) * DSH + c4 * 4) = *(const float4*)(p.R + (size_t)(tb + tk) * RS + c4 * 4);
;       }
.LBB0_1167:
	s_load_dwordx2 s[26:27], s[0:1], 0x190
	s_mov_b32 s21, 0x4ec4ec4f
	s_movk_i32 s22, 0xfe60
	v_mul_hi_u32 v39, v4, s21
	v_lshrrev_b32_e32 v39, 7, v39
	v_mad_i32_i24 v44, v39, s22, v4
	v_add_u32_e32 v45, s20, v39
	v_mul_u32_u24_e32 v45, 0x1c00, v45
	v_lshl_add_u32 v45, v44, 4, v45
	v_mul_u32_u24_e32 v70, 0x1a00, v39
	v_lshl_add_u32 v70, v44, 4, v70
	s_waitcnt lgkmcnt(0)
	global_load_dwordx4 v[46:49], v45, s[26:27]
	v_add_u32_e32 v38, 0x100, v4
	v_mul_hi_u32 v39, v38, s21
	v_lshrrev_b32_e32 v39, 7, v39
	v_mad_i32_i24 v44, v39, s22, v38
	v_add_u32_e32 v45, s20, v39
	v_mul_u32_u24_e32 v45, 0x1c00, v45
	v_lshl_add_u32 v45, v44, 4, v45
	v_mul_u32_u24_e32 v71, 0x1a00, v39
	v_lshl_add_u32 v71, v44, 4, v71
	global_load_dwordx4 v[50:53], v45, s[26:27]
	v_add_u32_e32 v38, 0x200, v4
	v_mul_hi_u32 v39, v38, s21
	v_lshrrev_b32_e32 v39, 7, v39
	v_mad_i32_i24 v44, v39, s22, v38
	v_add_u32_e32 v45, s20, v39
	v_mul_u32_u24_e32 v45, 0x1c00, v45
	v_lshl_add_u32 v45, v44, 4, v45
	v_mul_u32_u24_e32 v72, 0x1a00, v39
	v_lshl_add_u32 v72, v44, 4, v72
	global_load_dwordx4 v[54:57], v45, s[26:27]
	v_add_u32_e32 v38, 0x300, v4
	v_mul_hi_u32 v39, v38, s21
	v_lshrrev_b32_e32 v39, 7, v39
	v_mad_i32_i24 v44, v39, s22, v38
	v_add_u32_e32 v45, s20, v39
	v_mul_u32_u24_e32 v45, 0x1c00, v45
	v_lshl_add_u32 v45, v44, 4, v45
	v_mul_u32_u24_e32 v74, 0x1a00, v39
	v_lshl_add_u32 v74, v44, 4, v74
	global_load_dwordx4 v[58:61], v45, s[26:27]
	v_add_u32_e32 v38, 0x400, v4
	v_mul_hi_u32 v39, v38, s21
	v_lshrrev_b32_e32 v39, 7, v39
	v_mad_i32_i24 v44, v39, s22, v38
	v_add_u32_e32 v45, s20, v39
	v_mul_u32_u24_e32 v45, 0x1c00, v45
	v_lshl_add_u32 v45, v44, 4, v45
	v_mul_u32_u24_e32 v75, 0x1a00, v39
	v_lshl_add_u32 v75, v44, 4, v75
	global_load_dwordx4 v[62:65], v45, s[26:27]
	v_add_u32_e32 v38, 0x500, v4
	v_mul_hi_u32 v39, v38, s21
	v_lshrrev_b32_e32 v39, 7, v39
	v_mad_i32_i24 v44, v39, s22, v38
	v_add_u32_e32 v45, s20, v39
	v_mul_u32_u24_e32 v45, 0x1c00, v45
	v_lshl_add_u32 v45, v44, 4, v45
	v_mul_u32_u24_e32 v76, 0x1a00, v39
	v_lshl_add_u32 v76, v44, 4, v76
	global_load_dwordx4 v[66:69], v45, s[26:27]
	v_add_u32_e32 v38, 0x600, v4
	v_mul_hi_u32 v39, v38, s21
	v_lshrrev_b32_e32 v39, 7, v39
	v_mad_i32_i24 v44, v39, s22, v38
	v_add_u32_e32 v45, s20, v39
	v_mul_u32_u24_e32 v45, 0x1c00, v45
	v_lshl_add_u32 v45, v44, 4, v45
	v_mul_u32_u24_e32 v78, 0x1a00, v39
	v_lshl_add_u32 v78, v44, 4, v78
	global_load_dwordx4 v[88:91], v45, s[26:27]
	v_add_u32_e32 v38, 0x700, v4
	v_mul_hi_u32 v39, v38, s21
	v_lshrrev_b32_e32 v39, 7, v39
	v_mad_i32_i24 v44, v39, s22, v38
	v_add_u32_e32 v45, s20, v39
	v_mul_u32_u24_e32 v45, 0x1c00, v45
	v_lshl_add_u32 v45, v44, 4, v45
	v_mul_u32_u24_e32 v79, 0x1a00, v39
	v_lshl_add_u32 v79, v44, 4, v79
	global_load_dwordx4 v[92:95], v45, s[26:27]
	v_add_u32_e32 v38, 0x800, v4
	v_mul_hi_u32 v39, v38, s21
	v_lshrrev_b32_e32 v39, 7, v39
	v_mad_i32_i24 v44, v39, s22, v38
	v_add_u32_e32 v45, s20, v39
	v_mul_u32_u24_e32 v45, 0x1c00, v45
	v_lshl_add_u32 v45, v44, 4, v45
	v_mul_u32_u24_e32 v80, 0x1a00, v39
	v_lshl_add_u32 v80, v44, 4, v80
	global_load_dwordx4 v[96:99], v45, s[26:27]
	v_add_u32_e32 v38, 0x900, v4
	v_mul_hi_u32 v39, v38, s21
	v_lshrrev_b32_e32 v39, 7, v39
	v_mad_i32_i24 v44, v39, s22, v38
	v_add_u32_e32 v45, s20, v39
	v_mul_u32_u24_e32 v45, 0x1c00, v45
	v_lshl_add_u32 v45, v44, 4, v45
	v_mul_u32_u24_e32 v81, 0x1a00, v39
	v_lshl_add_u32 v81, v44, 4, v81
	global_load_dwordx4 v[100:103], v45, s[26:27]
	v_add_u32_e32 v38, 0xa00, v4
	v_mul_hi_u32 v39, v38, s21
	v_lshrrev_b32_e32 v39, 7, v39
	v_mad_i32_i24 v44, v39, s22, v38
	v_add_u32_e32 v45, s20, v39
	v_mul_u32_u24_e32 v45, 0x1c00, v45
	v_lshl_add_u32 v45, v44, 4, v45
	v_mul_u32_u24_e32 v82, 0x1a00, v39
	v_lshl_add_u32 v82, v44, 4, v82
	global_load_dwordx4 v[108:111], v45, s[26:27]
	v_add_u32_e32 v38, 0xb00, v4
	v_mul_hi_u32 v39, v38, s21
	v_lshrrev_b32_e32 v39, 7, v39
	v_mad_i32_i24 v44, v39, s22, v38
	v_add_u32_e32 v45, s20, v39
	v_mul_u32_u24_e32 v45, 0x1c00, v45
	v_lshl_add_u32 v45, v44, 4, v45
	v_mul_u32_u24_e32 v83, 0x1a00, v39
	v_lshl_add_u32 v83, v44, 4, v83
	global_load_dwordx4 v[112:115], v45, s[26:27]
	v_add_u32_e32 v38, 0xc00, v4
	v_mul_hi_u32 v39, v38, s21
	v_lshrrev_b32_e32 v39, 7, v39
	v_mad_i32_i24 v44, v39, s22, v38
	v_add_u32_e32 v45, s20, v39
	v_mul_u32_u24_e32 v45, 0x1c00, v45
	v_lshl_add_u32 v45, v44, 4, v45
	v_mul_u32_u24_e32 v84, 0x1a00, v39
	v_lshl_add_u32 v84, v44, 4, v84
	global_load_dwordx4 v[116:119], v45, s[26:27]
	s_waitcnt vmcnt(12)
	ds_write_b128 v70, v[46:49] offset:6656
	s_waitcnt vmcnt(11)
	ds_write_b128 v71, v[50:53] offset:6656
	s_waitcnt vmcnt(10)
	ds_write_b128 v72, v[54:57] offset:6656
	s_waitcnt vmcnt(9)
	ds_write_b128 v74, v[58:61] offset:6656
	s_waitcnt vmcnt(8)
	ds_write_b128 v75, v[62:65] offset:6656
	s_waitcnt vmcnt(7)
	ds_write_b128 v76, v[66:69] offset:6656
	s_waitcnt vmcnt(6)
	ds_write_b128 v78, v[88:91] offset:6656
	s_waitcnt vmcnt(5)
	ds_write_b128 v79, v[92:95] offset:6656
	s_waitcnt vmcnt(4)
	ds_write_b128 v80, v[96:99] offset:6656
	s_waitcnt vmcnt(3)
	ds_write_b128 v81, v[100:103] offset:6656
	s_waitcnt vmcnt(2)
	ds_write_b128 v82, v[108:111] offset:6656
	s_waitcnt vmcnt(1)
	ds_write_b128 v83, v[112:115] offset:6656
	s_waitcnt vmcnt(0)
	ds_write_b128 v84, v[116:119] offset:6656

; DI void scan_task(const Params& p, int l, int isP, int b, int h, int rg, char* smem, const bool dry) {
;     ...
;   const int i = rg * 16 + wave * 4 + g4;
;   f32x2 Sa = {0.f, 0.f}, Sb = {0.f, 0.f};
;   if (!isP) {
;     const float4 s = *(const float4*)(p.state_wkv + ((size_t)((l * 32 + b) * 8 + h) * 64 + i) * 64 + jq * 4);
;     Sa = (f32x2){s.x, s.y}; Sb = (f32x2){s.z, s.w};
;   }
;   __builtin_amdgcn_s_setprio(3);
;   const int ds = tid >> 4, dj = tid & 15;
;   const int lst = (tid >> 3) & 31, lch = tid & 7;
;   float4 rd0, rd1;
;   uint4 qr, qk, qa, qb, rv;
;   const int nch = T >> 5;
;   auto gload = [&](int c) {
;     const int tk = tokbase + c * 32;
;     rd0 = *(const float4*)(p.R + (size_t)(tk + ds) * RS + h * 64 + dj * 4);
;     rd1 = *(const float4*)(p.R + (size_t)(tk + 16 + ds) * RS + h * 64 + dj * 4);
;     const bf16_t* rb = (const bf16_t*)(p.R + (size_t)(tk + lst) * RS + 512) + h * 64 + lch * 8;
;     qr = *(const uint4*)(rb);
;     qk = *(const uint4*)(rb + 512);
;     qa = *(const uint4*)(rb + 1536);
;     qb = *(const uint4*)(rb + 2048);
;     if (tid < 64) {
;       const int s = tid >> 1, half = tid & 1;
;       rv = *(const uint4*)((const bf16_t*)(p.R + (size_t)(tk + s) * RS + 512) + 1024 + h * 64 + rg * 16 + half * 8);
;     }
;   };
;     ...
;   auto sstore = [&](int bi) {
;     char* bb = smem + bi * BUFB;
;     *(float4*)(bb + (ds * 64 + dj * 4) * 4) = rd0;
;     *(float4*)(bb + ((16 + ds) * 64 + dj * 4) * 4) = rd1;
;     {
;       CVT8(qa, alo, ahi)
;       float* d = (float*)(bb + 8192) + lst * 64 + lch * 8;
;       *(float4*)d = alo; *(float4*)(d + 4) = ahi;
;     }
;     {
;       CVT8(qb, blo, bhi)
;       float* d = (float*)(bb + 16384) + lst * 64 + lch * 8;
;       *(float4*)d = blo; *(float4*)(d + 4) = bhi;
;     }
;     *(uint4*)(bb + 24576 + (lst * 64 + lch * 8) * 2) = qr;
;     *(uint4*)(bb + 28672 + (lst * 64 + lch * 8) * 2) = qk;
;     if (tid < 64) {
;       const int s = tid >> 1, half = tid & 1;
;       CVT8(rv, vlo, vhi)
;       float* d = (float*)(bb + 32768) + s * 16 + half * 8;
;       *(float4*)d = vlo; *(float4*)(d + 4) = vhi;
;     }
;   };
;     ...
;   __syncthreads();
;   gload(0);
;   sstore(0);
;   __syncthreads();
.LBB0_1529:
	s_add_i32 s4, s93, 0xfffffa20
	s_cmp_gt_i32 s93, 63
	s_cselect_b32 s5, s4, s93
	s_cselect_b64 s[46:47], -1, 0
	s_cselect_b32 s17, 4, 0x200
	s_bfe_u32 s4, s5, 0x30002
	s_and_b32 s6, s5, 3
	s_lshr_b32 s5, s5, 5
	v_readlane_b32 s7, v254, 51
	s_lshl_b32 s8, s5, 13
	s_lshl_b32 s9, s5, 6
	s_addk_i32 s9, 0x4000
	s_cmp_gt_i32 s93, 63
	s_cselect_b32 s8, s9, s8
	s_load_dwordx2 s[12:13], s[0:1], 0x190
	s_load_dwordx2 s[14:15], s[0:1], 0x198
	s_load_dwordx2 s[10:11], s[0:1], 0x30
	s_load_dwordx2 s[24:25], s[0:1], 0xe8
	s_mul_i32 s9, s8, 0x1c00
	s_lshl_b32 s16, s8, 11
	v_and_b32_e32 v66, 15, v182
	v_lshrrev_b32_e32 v67, 4, v182
	v_mul_u32_u24_e32 v68, 0x1c00, v67
	v_lshlrev_b32_e32 v76, 4, v66
	v_lshlrev_b32_e32 v77, 6, v67
	v_lshlrev_b32_e32 v78, 4, v182
	v_lshlrev_b32_e32 v79, 6, v66
	v_lshl_add_u32 v79, v67, 2, v79
	s_lshl_b32 s18, s4, 8
	v_lshl_add_u32 v80, v66, 4, v68
	v_add_u32_e32 v80, s18, v80
	s_lshl_b32 s18, s4, 7
	s_addk_i32 s18, 0xc00
	v_lshl_add_u32 v81, v66, 3, v68
	v_add_u32_e32 v81, s18, v81
	s_lshl_b32 s19, s6, 5
	s_add_i32 s18, s18, s19
	s_addk_i32 s18, 0x400
	v_lshl_add_u32 v82, v66, 1, v68
	v_add_u32_e32 v82, s18, v82
	s_lshl_b32 s18, s4, 8
	s_lshl_b32 s19, s6, 6
	s_add_i32 s18, s18, s19
	v_and_b32_e32 v83, 3, v66
	v_lshlrev_b32_e32 v83, 2, v83
	v_bfe_u32 v70, v66, 2, 1
	v_lshl_add_u32 v83, v70, 1, v83
	v_bfe_u32 v70, v66, 3, 1
	v_add_u32_e32 v83, v70, v83
	v_lshlrev_b32_e32 v83, 11, v83
	v_lshl_add_u32 v83, v67, 2, v83
	v_add_u32_e32 v83, s18, v83
	s_lshl_b32 s18, s6, 12
	v_lshlrev_b32_e32 v69, 8, v67
	v_lshl_add_u32 v69, v66, 4, v69
	v_add_u32_e32 v69, s18, v69
	v_and_b32_e32 v70, 1, v182
	v_and_b32_e32 v71, 2, v182
	v_cmp_ne_u32_e64 s[18:19], 0, v70
	v_cmp_ne_u32_e64 s[20:21], 0, v71
	s_lshl_b32 s26, s7, 5
	s_add_i32 s26, s26, s5
	s_lshl_b32 s26, s26, 3
	s_add_i32 s26, s26, s4
	s_lshl_b32 s26, s26, 14
	s_lshl_b32 s27, s7, 1
	s_add_i32 s27, s27, s5
	s_lshl_b32 s27, s27, 3
	s_add_i32 s27, s27, s4
	s_lshl_b32 s27, s27, 14
	s_waitcnt lgkmcnt(0)
	s_add_u32 s12, s12, s9
	s_addc_u32 s13, s13, 0
	s_add_u32 s14, s14, s16
	s_addc_u32 s15, s15, 0
	s_add_u32 s10, s10, s26
	s_addc_u32 s11, s11, 0
	s_add_u32 s26, s26, 0x7986800
	s_add_u32 s27, s27, 0x7000000
	s_cmp_gt_i32 s93, 63
	s_cselect_b32 s26, s26, s27
	s_add_u32 s24, s24, s26
	s_addc_u32 s25, s25, 0
	v_mov_b32_e32 v4, 0
	v_mov_b32_e32 v5, 0
	v_mov_b32_e32 v6, 0
	v_mov_b32_e32 v7, 0
	s_cmp_gt_i32 s93, 63
	s_cbranch_scc0 .Lscan_nostate
	global_load_dwordx4 v[4:7], v69, s[10:11]
.Lscan_nostate:
	v_mov_b32_e32 v59, v69
	s_setprio 3
	s_barrier
	global_load_dwordx4 v[84:87], v80, s[12:13]
	global_load_dwordx2 v[88:89], v81, s[12:13] offset:-1024
	global_load_dwordx2 v[90:91], v81, s[12:13]
	global_load_dwordx2 v[92:93], v81, s[12:13] offset:2048
	global_load_dwordx2 v[94:95], v81, s[12:13] offset:3072
	global_load_ushort v96, v82, s[12:13]
	s_add_u32 s12, s12, 0x1c000
	s_addc_u32 s13, s13, 0
	global_load_dwordx4 v[100:103], v80, s[12:13]
	global_load_dwordx2 v[104:105], v81, s[12:13] offset:-1024
	global_load_dwordx2 v[106:107], v81, s[12:13]
	global_load_dwordx2 v[108:109], v81, s[12:13] offset:2048
	global_load_dwordx2 v[98:99], v81, s[12:13] offset:3072
	global_load_ushort v97, v82, s[12:13]
	s_add_u32 s12, s12, 0x1c000
	s_addc_u32 s13, s13, 0
	s_waitcnt vmcnt(6)
	ds_write_b128 v78, v[84:87] offset:0
	v_lshlrev_b32_e32 v8, 16, v92
	v_and_b32_e32 v9, 0xffff0000, v92
	v_lshlrev_b32_e32 v10, 16, v93
	v_and_b32_e32 v11, 0xffff0000, v93
	ds_write_b128 v78, v[8:11] offset:4096
	v_lshlrev_b32_e32 v12, 16, v94
	v_and_b32_e32 v13, 0xffff0000, v94
	v_lshlrev_b32_e32 v14, 16, v95
	v_and_b32_e32 v15, 0xffff0000, v95
	ds_write_b128 v78, v[12:15] offset:8192
	v_lshlrev_b32_e32 v16, 16, v88
	v_and_b32_e32 v17, 0xffff0000, v88
	v_lshlrev_b32_e32 v18, 16, v89
	v_and_b32_e32 v19, 0xffff0000, v89
	ds_write_b128 v78, v[16:19] offset:12288
	v_lshlrev_b32_e32 v20, 16, v90
	v_and_b32_e32 v21, 0xffff0000, v90
	v_lshlrev_b32_e32 v22, 16, v91
	v_and_b32_e32 v23, 0xffff0000, v91
	ds_write_b128 v78, v[20:23] offset:16384
	v_lshlrev_b32_e32 v24, 16, v96
	ds_write_b32 v79, v24 offset:20480
	s_waitcnt lgkmcnt(0)
	s_barrier
	ds_read_b128 v[12:15], v76 offset:4096
	ds_read_b128 v[24:27], v76 offset:16384
	ds_read_b128 v[48:51], v77 offset:20480
	ds_read_b128 v[8:11], v76 offset:0
	ds_read_b128 v[16:19], v76 offset:8192
	ds_read_b128 v[20:23], v76 offset:12288
	ds_read_b128 v[32:35], v76 offset:4352
	ds_read_b128 v[44:47], v76 offset:16640
	ds_read_b128 v[28:31], v76 offset:256
	ds_read_b128 v[36:39], v76 offset:8448
	ds_read_b128 v[40:43], v76 offset:12544
	s_mov_b32 s16, 0
.Lscan_loop:
.Lscan_bodyA:
	s_add_i32 s23, s16, 2
	s_cmp_lt_u32 s23, s17
	s_cselect_b32 s22, 1, 0
	s_cbranch_scc0 .Lscan_noldA
	global_load_dwordx4 v[84:87], v80, s[12:13]
	global_load_dwordx2 v[88:89], v81, s[12:13] offset:-1024
	global_load_dwordx2 v[90:91], v81, s[12:13]
	global_load_dwordx2 v[92:93], v81, s[12:13] offset:2048
	global_load_dwordx2 v[94:95], v81, s[12:13] offset:3072
	global_load_ushort v96, v82, s[12:13]
	s_add_u32 s12, s12, 0x1c000
	s_addc_u32 s13, s13, 0
; DI void scan_task(const Params& p, int l, int isP, int b, int h, int rg, char* smem, const bool dry) {
;     ...
;     f32x4 w4 = *(const f32x4*)fw, a4 = *(const f32x4*)fa, b4 = *(const f32x4*)fb;
;     uint2 ur = *(const uint2*)pr, uk = *(const uint2*)pk;
;     float v = vb[0];
; #pragma unroll
;     for (int s = 0; s < 32; s++) {
;       f32x4 w4n = w4, a4n = a4, b4n = b4;
;       uint2 urn = ur, ukn = uk;
;       float vn = v;
;       if (s < 31) {
;         w4n = *(const f32x4*)(fw + (s + 1) * 64);
;         a4n = *(const f32x4*)(fa + (s + 1) * 64);
;         b4n = *(const f32x4*)(fb + (s + 1) * 64);
;         urn = *(const uint2*)(pr + (s + 1) * 128);
;         ukn = *(const uint2*)(pk + (s + 1) * 128);
;         vn = vb[(s + 1) * 16];
;       }
;       __builtin_amdgcn_sched_barrier(0);
;       const f32x2 klo = {__uint_as_float(uk.x << 16), __uint_as_float(uk.x & 0xFFFF0000u)};
;       const f32x2 khi = {__uint_as_float(uk.y << 16), __uint_as_float(uk.y & 0xFFFF0000u)};
;       const f32x2 rlo = {__uint_as_float(ur.x << 16), __uint_as_float(ur.x & 0xFFFF0000u)};
;       const f32x2 rhi = {__uint_as_float(ur.y << 16), __uint_as_float(ur.y & 0xFFFF0000u)};
;       const f32x2 vv = {v, v};
;       const f32x2 t = Sa * a4.lo + Sb * a4.hi;
;       const f32x2 na = Sa * w4.lo + vv * klo;
;       const f32x2 nb = Sb * w4.hi + vv * khi;
;       float sa = t.x + t.y;
;       float yp = yprev;
;       rowsum16x2(sa, yp);
;       if (s >= 1 && s <= 16) ykeep0 = (jq == s - 1) ? yp : ykeep0;
;       if (s >= 17) ykeep1 = (jq == s - 17) ? yp : ykeep1;
;       const f32x2 sv = {sa, sa};
;       Sa = na + sv * b4.lo;
;       Sb = nb + sv * b4.hi;
;       const f32x2 yy = Sa * rlo + Sb * rhi;
;       yprev = yy.x + yy.y;
;       w4 = w4n; a4 = a4n; b4 = b4n; ur = urn; uk = ukn; v = vn;
;     }
.Lscan_noldA:
	s_waitcnt lgkmcnt(6)
	v_pk_mul_f32 v[56:57], v[4:5], v[12:13]
	v_pk_fma_f32 v[56:57], v[6:7], v[14:15], v[56:57]
	ds_read_b128 v[12:15], v76 offset:4608
	v_add_f32_e32 v58, v56, v57
	v_pk_mul_f32 v[60:61], v[48:49], v[24:25] op_sel_hi:[0,1]
	v_pk_mul_f32 v[62:63], v[48:49], v[26:27] op_sel_hi:[0,1]
	v_add_f32_dpp v58, v58, v58 quad_perm:[1,0,3,2] row_mask:0xf bank_mask:0xf bound_ctrl:1
	ds_read_b128 v[24:27], v76 offset:16896
	s_nop 0
	v_add_f32_dpp v58, v58, v58 quad_perm:[2,3,0,1] row_mask:0xf bank_mask:0xf bound_ctrl:1
	v_pk_fma_f32 v[60:61], v[4:5], v[8:9], v[60:61]
	v_pk_fma_f32 v[62:63], v[6:7], v[10:11], v[62:63]
	v_add_f32_dpp v58, v58, v58 row_half_mirror row_mask:0xf bank_mask:0xf bound_ctrl:1
	ds_read_b128 v[8:11], v76 offset:512
	s_nop 0
	v_add_f32_dpp v58, v58, v58 row_mirror row_mask:0xf bank_mask:0xf bound_ctrl:1
	v_pk_fma_f32 v[4:5], v[58:59], v[16:17], v[60:61] op_sel_hi:[0,1,1]
	v_pk_fma_f32 v[6:7], v[58:59], v[18:19], v[62:63] op_sel_hi:[0,1,1]
	ds_read_b128 v[16:19], v76 offset:8704
	s_waitcnt lgkmcnt(5)
	v_pk_mul_f32 v[56:57], v[4:5], v[32:33]
	v_pk_mul_f32 v[64:65], v[4:5], v[20:21]
	v_pk_fma_f32 v[56:57], v[6:7], v[34:35], v[56:57]
	ds_read_b128 v[32:35], v76 offset:4864
	v_pk_fma_f32 v[64:65], v[6:7], v[22:23], v[64:65]
	ds_read_b128 v[20:23], v76 offset:12800
	v_add_f32_e32 v58, v56, v57
	v_pk_mul_f32 v[60:61], v[48:49], v[44:45] op_sel:[1,0] op_sel_hi:[1,1]
	v_pk_mul_f32 v[62:63], v[48:49], v[46:47] op_sel:[1,0] op_sel_hi:[1,1]
	v_add_f32_dpp v58, v58, v58 quad_perm:[1,0,3,2] row_mask:0xf bank_mask:0xf bound_ctrl:1
	ds_read_b128 v[44:47], v76 offset:17152
	v_add_f32_e32 v66, v64, v65
	ds_read_b128 v[52:55], v77 offset:20496
	v_add_f32_dpp v58, v58, v58 quad_perm:[2,3,0,1] row_mask:0xf bank_mask:0xf bound_ctrl:1
	v_pk_fma_f32 v[60:61], v[4:5], v[28:29], v[60:61]
	v_pk_fma_f32 v[62:63], v[6:7], v[30:31], v[62:63]
	v_add_f32_dpp v58, v58, v58 row_half_mirror row_mask:0xf bank_mask:0xf bound_ctrl:1
	ds_read_b128 v[28:31], v76 offset:768
	s_nop 0
	v_add_f32_dpp v58, v58, v58 row_mirror row_mask:0xf bank_mask:0xf bound_ctrl:1
	v_pk_fma_f32 v[4:5], v[58:59], v[36:37], v[60:61] op_sel_hi:[0,1,1]
	v_pk_fma_f32 v[6:7], v[58:59], v[38:39], v[62:63] op_sel_hi:[0,1,1]
	ds_read_b128 v[36:39], v76 offset:8960
	s_waitcnt lgkmcnt(6)
	v_pk_mul_f32 v[56:57], v[4:5], v[12:13]
	v_pk_mul_f32 v[64:65], v[4:5], v[40:41]
	v_pk_fma_f32 v[56:57], v[6:7], v[14:15], v[56:57]
	ds_read_b128 v[12:15], v76 offset:5120
	v_pk_fma_f32 v[64:65], v[6:7], v[42:43], v[64:65]
	ds_read_b128 v[40:43], v76 offset:13056
	v_add_f32_e32 v58, v56, v57
	v_pk_mul_f32 v[60:61], v[50:51], v[24:25] op_sel_hi:[0,1]
	v_pk_mul_f32 v[62:63], v[50:51], v[26:27] op_sel_hi:[0,1]
	v_add_f32_dpp v58, v58, v58 quad_perm:[1,0,3,2] row_mask:0xf bank_mask:0xf bound_ctrl:1
	ds_read_b128 v[24:27], v76 offset:17408
	v_add_f32_e32 v67, v64, v65
	v_add_f32_dpp v58, v58, v58 quad_perm:[2,3,0,1] row_mask:0xf bank_mask:0xf bound_ctrl:1
	v_pk_fma_f32 v[60:61], v[4:5], v[8:9], v[60:61]
	v_pk_fma_f32 v[62:63], v[6:7], v[10:11], v[62:63]
	v_add_f32_dpp v68, v66, v66 row_mirror row_mask:0xf bank_mask:0x3
	v_add_f32_dpp v58, v58, v58 row_half_mirror row_mask:0xf bank_mask:0xf bound_ctrl:1
	ds_read_b128 v[8:11], v76 offset:1024
	v_add_f32_dpp v68, v67, v67 row_mirror row_mask:0xf bank_mask:0xc
	v_add_f32_dpp v58, v58, v58 row_mirror row_mask:0xf bank_mask:0xf bound_ctrl:1
	v_pk_fma_f32 v[4:5], v[58:59], v[16:17], v[60:61] op_sel_hi:[0,1,1]
	v_pk_fma_f32 v[6:7], v[58:59], v[18:19], v[62:63] op_sel_hi:[0,1,1]
	ds_read_b128 v[16:19], v76 offset:9216
	s_waitcnt lgkmcnt(5)
	v_pk_mul_f32 v[56:57], v[4:5], v[32:33]
	v_pk_mul_f32 v[64:65], v[4:5], v[20:21]
	v_pk_fma_f32 v[56:57], v[6:7], v[34:35], v[56:57]
	ds_read_b128 v[32:35], v76 offset:5376
	v_pk_fma_f32 v[64:65], v[6:7], v[22:23], v[64:65]
	ds_read_b128 v[20:23], v76 offset:13312
	v_add_f32_e32 v58, v56, v57
	v_pk_mul_f32 v[60:61], v[50:51], v[44:45] op_sel:[1,0] op_sel_hi:[1,1]
	v_pk_mul_f32 v[62:63], v[50:51], v[46:47] op_sel:[1,0] op_sel_hi:[1,1]
	v_add_f32_dpp v58, v58, v58 quad_perm:[1,0,3,2] row_mask:0xf bank_mask:0xf bound_ctrl:1
	ds_read_b128 v[44:47], v76 offset:17664
	v_add_f32_e32 v66, v64, v65
	v_add_f32_dpp v58, v58, v58 quad_perm:[2,3,0,1] row_mask:0xf bank_mask:0xf bound_ctrl:1
	v_pk_fma_f32 v[60:61], v[4:5], v[28:29], v[60:61]
	v_pk_fma_f32 v[62:63], v[6:7], v[30:31], v[62:63]
	v_add_f32_dpp v58, v58, v58 row_half_mirror row_mask:0xf bank_mask:0xf bound_ctrl:1
	ds_read_b128 v[28:31], v76 offset:1280
	s_nop 0
	v_add_f32_dpp v58, v58, v58 row_mirror row_mask:0xf bank_mask:0xf bound_ctrl:1
	v_pk_fma_f32 v[4:5], v[58:59], v[36:37], v[60:61] op_sel_hi:[0,1,1]
	v_pk_fma_f32 v[6:7], v[58:59], v[38:39], v[62:63] op_sel_hi:[0,1,1]
	ds_read_b128 v[36:39], v76 offset:9472
	s_waitcnt lgkmcnt(5)
	v_pk_mul_f32 v[56:57], v[4:5], v[12:13]
	v_pk_mul_f32 v[64:65], v[4:5], v[40:41]
	v_pk_fma_f32 v[56:57], v[6:7], v[14:15], v[56:57]
	ds_read_b128 v[12:15], v76 offset:5632
	v_pk_fma_f32 v[64:65], v[6:7], v[42:43], v[64:65]
	ds_read_b128 v[40:43], v76 offset:13568
	v_add_f32_e32 v58, v56, v57
	v_pk_mul_f32 v[60:61], v[52:53], v[24:25] op_sel_hi:[0,1]
	v_pk_mul_f32 v[62:63], v[52:53], v[26:27] op_sel_hi:[0,1]
	v_add_f32_dpp v58, v58, v58 quad_perm:[1,0,3,2] row_mask:0xf bank_mask:0xf bound_ctrl:1
	ds_read_b128 v[24:27], v76 offset:17920
	v_add_f32_e32 v67, v64, v65
	v_add_f32_dpp v58, v58, v58 quad_perm:[2,3,0,1] row_mask:0xf bank_mask:0xf bound_ctrl:1
	v_pk_fma_f32 v[60:61], v[4:5], v[8:9], v[60:61]
	v_pk_fma_f32 v[62:63], v[6:7], v[10:11], v[62:63]
	v_add_f32_dpp v69, v66, v66 row_mirror row_mask:0xf bank_mask:0x3
	v_add_f32_dpp v58, v58, v58 row_half_mirror row_mask:0xf bank_mask:0xf bound_ctrl:1
	ds_read_b128 v[8:11], v76 offset:1536
	v_add_f32_dpp v69, v67, v67 row_mirror row_mask:0xf bank_mask:0xc
	v_add_f32_dpp v58, v58, v58 row_mirror row_mask:0xf bank_mask:0xf bound_ctrl:1
	v_pk_fma_f32 v[4:5], v[58:59], v[16:17], v[60:61] op_sel_hi:[0,1,1]
	v_pk_fma_f32 v[6:7], v[58:59], v[18:19], v[62:63] op_sel_hi:[0,1,1]
	ds_read_b128 v[16:19], v76 offset:9728
	s_waitcnt lgkmcnt(5)
; DI void scan_task(const Params& p, int l, int isP, int b, int h, int rg, char* smem, const bool dry) {
;     ...
; #pragma unroll
;     for (int s = 0; s < 32; s++) {
;       f32x4 w4n = w4, a4n = a4, b4n = b4;
;       uint2 urn = ur, ukn = uk;
;       float vn = v;
;       if (s < 31) {
;         w4n = *(const f32x4*)(fw + (s + 1) * 64);
;         a4n = *(const f32x4*)(fa + (s + 1) * 64);
;         b4n = *(const f32x4*)(fb + (s + 1) * 64);
;         urn = *(const uint2*)(pr + (s + 1) * 128);
;         ukn = *(const uint2*)(pk + (s + 1) * 128);
;         vn = vb[(s + 1) * 16];
;       }
;       __builtin_amdgcn_sched_barrier(0);
;       const f32x2 klo = {__uint_as_float(uk.x << 16), __uint_as_float(uk.x & 0xFFFF0000u)};
;       const f32x2 khi = {__uint_as_float(uk.y << 16), __uint_as_float(uk.y & 0xFFFF0000u)};
;       const f32x2 rlo = {__uint_as_float(ur.x << 16), __uint_as_float(ur.x & 0xFFFF0000u)};
;       const f32x2 rhi = {__uint_as_float(ur.y << 16), __uint_as_float(ur.y & 0xFFFF0000u)};
;       const f32x2 vv = {v, v};
;       const f32x2 t = Sa * a4.lo + Sb * a4.hi;
;       const f32x2 na = Sa * w4.lo + vv * klo;
;       const f32x2 nb = Sb * w4.hi + vv * khi;
;       float sa = t.x + t.y;
;       float yp = yprev;
;       rowsum16x2(sa, yp);
;       if (s >= 1 && s <= 16) ykeep0 = (jq == s - 1) ? yp : ykeep0;
;       if (s >= 17) ykeep1 = (jq == s - 17) ? yp : ykeep1;
;       const f32x2 sv = {sa, sa};
;       Sa = na + sv * b4.lo;
;       Sb = nb + sv * b4.hi;
;       const f32x2 yy = Sa * rlo + Sb * rhi;
;       yprev = yy.x + yy.y;
;       w4 = w4n; a4 = a4n; b4 = b4n; ur = urn; uk = ukn; v = vn;
;     }
	v_pk_mul_f32 v[56:57], v[4:5], v[32:33]
	v_pk_mul_f32 v[64:65], v[4:5], v[20:21]
	v_pk_fma_f32 v[56:57], v[6:7], v[34:35], v[56:57]
	ds_read_b128 v[32:35], v76 offset:5888
	v_pk_fma_f32 v[64:65], v[6:7], v[22:23], v[64:65]
	ds_read_b128 v[20:23], v76 offset:13824
	v_add_f32_e32 v58, v56, v57
	v_pk_mul_f32 v[60:61], v[52:53], v[44:45] op_sel:[1,0] op_sel_hi:[1,1]
	v_pk_mul_f32 v[62:63], v[52:53], v[46:47] op_sel:[1,0] op_sel_hi:[1,1]
	v_add_f32_dpp v58, v58, v58 quad_perm:[1,0,3,2] row_mask:0xf bank_mask:0xf bound_ctrl:1
	ds_read_b128 v[44:47], v76 offset:18176
	v_add_f32_e32 v66, v64, v65
	ds_read_b128 v[48:51], v77 offset:20512
	v_add_f32_dpp v58, v58, v58 quad_perm:[2,3,0,1] row_mask:0xf bank_mask:0xf bound_ctrl:1
	v_pk_fma_f32 v[60:61], v[4:5], v[28:29], v[60:61]
	v_pk_fma_f32 v[62:63], v[6:7], v[30:31], v[62:63]
	v_add_f32_dpp v68, v68, v68 row_half_mirror row_mask:0xf bank_mask:0x5
	v_add_f32_dpp v58, v58, v58 row_half_mirror row_mask:0xf bank_mask:0xf bound_ctrl:1
	ds_read_b128 v[28:31], v76 offset:1792
	v_add_f32_dpp v68, v69, v69 row_half_mirror row_mask:0xf bank_mask:0xa
	v_add_f32_dpp v58, v58, v58 row_mirror row_mask:0xf bank_mask:0xf bound_ctrl:1
	v_pk_fma_f32 v[4:5], v[58:59], v[36:37], v[60:61] op_sel_hi:[0,1,1]
	v_pk_fma_f32 v[6:7], v[58:59], v[38:39], v[62:63] op_sel_hi:[0,1,1]
	ds_read_b128 v[36:39], v76 offset:9984
	s_waitcnt lgkmcnt(6)
	v_pk_mul_f32 v[56:57], v[4:5], v[12:13]
	v_pk_mul_f32 v[64:65], v[4:5], v[40:41]
	v_pk_fma_f32 v[56:57], v[6:7], v[14:15], v[56:57]
	ds_read_b128 v[12:15], v76 offset:6144
	v_pk_fma_f32 v[64:65], v[6:7], v[42:43], v[64:65]
	ds_read_b128 v[40:43], v76 offset:14080
	v_add_f32_e32 v58, v56, v57
	v_pk_mul_f32 v[60:61], v[54:55], v[24:25] op_sel_hi:[0,1]
	v_pk_mul_f32 v[62:63], v[54:55], v[26:27] op_sel_hi:[0,1]
	v_add_f32_dpp v58, v58, v58 quad_perm:[1,0,3,2] row_mask:0xf bank_mask:0xf bound_ctrl:1
	ds_read_b128 v[24:27], v76 offset:18432
	v_add_f32_e32 v67, v64, v65
	v_add_f32_dpp v58, v58, v58 quad_perm:[2,3,0,1] row_mask:0xf bank_mask:0xf bound_ctrl:1
	v_pk_fma_f32 v[60:61], v[4:5], v[8:9], v[60:61]
	v_pk_fma_f32 v[62:63], v[6:7], v[10:11], v[62:63]
	v_add_f32_dpp v70, v66, v66 row_mirror row_mask:0xf bank_mask:0x3
	v_add_f32_dpp v58, v58, v58 row_half_mirror row_mask:0xf bank_mask:0xf bound_ctrl:1
	ds_read_b128 v[8:11], v76 offset:2048
	v_add_f32_dpp v70, v67, v67 row_mirror row_mask:0xf bank_mask:0xc
	v_add_f32_dpp v58, v58, v58 row_mirror row_mask:0xf bank_mask:0xf bound_ctrl:1
	v_pk_fma_f32 v[4:5], v[58:59], v[16:17], v[60:61] op_sel_hi:[0,1,1]
	v_pk_fma_f32 v[6:7], v[58:59], v[18:19], v[62:63] op_sel_hi:[0,1,1]
	ds_read_b128 v[16:19], v76 offset:10240
	s_waitcnt lgkmcnt(5)
	v_pk_mul_f32 v[56:57], v[4:5], v[32:33]
	v_pk_mul_f32 v[64:65], v[4:5], v[20:21]
	v_pk_fma_f32 v[56:57], v[6:7], v[34:35], v[56:57]
	ds_read_b128 v[32:35], v76 offset:6400
	v_pk_fma_f32 v[64:65], v[6:7], v[22:23], v[64:65]
	ds_read_b128 v[20:23], v76 offset:14336
	v_add_f32_e32 v58, v56, v57
	v_pk_mul_f32 v[60:61], v[54:55], v[44:45] op_sel:[1,0] op_sel_hi:[1,1]
	v_pk_mul_f32 v[62:63], v[54:55], v[46:47] op_sel:[1,0] op_sel_hi:[1,1]
	v_add_f32_dpp v58, v58, v58 quad_perm:[1,0,3,2] row_mask:0xf bank_mask:0xf bound_ctrl:1
	ds_read_b128 v[44:47], v76 offset:18688
	v_add_f32_e32 v66, v64, v65
	v_add_f32_dpp v58, v58, v58 quad_perm:[2,3,0,1] row_mask:0xf bank_mask:0xf bound_ctrl:1
	v_pk_fma_f32 v[60:61], v[4:5], v[28:29], v[60:61]
	v_pk_fma_f32 v[62:63], v[6:7], v[30:31], v[62:63]
	v_add_f32_dpp v58, v58, v58 row_half_mirror row_mask:0xf bank_mask:0xf bound_ctrl:1
	ds_read_b128 v[28:31], v76 offset:2304
	s_nop 0
	v_add_f32_dpp v58, v58, v58 row_mirror row_mask:0xf bank_mask:0xf bound_ctrl:1
	v_pk_fma_f32 v[4:5], v[58:59], v[36:37], v[60:61] op_sel_hi:[0,1,1]
	v_pk_fma_f32 v[6:7], v[58:59], v[38:39], v[62:63] op_sel_hi:[0,1,1]
	ds_read_b128 v[36:39], v76 offset:10496
	s_waitcnt lgkmcnt(5)
	v_pk_mul_f32 v[56:57], v[4:5], v[12:13]
	v_pk_mul_f32 v[64:65], v[4:5], v[40:41]
	v_pk_fma_f32 v[56:57], v[6:7], v[14:15], v[56:57]
	ds_read_b128 v[12:15], v76 offset:6656
	v_pk_fma_f32 v[64:65], v[6:7], v[42:43], v[64:65]
	ds_read_b128 v[40:43], v76 offset:14592
	v_add_f32_e32 v58, v56, v57
	v_pk_mul_f32 v[60:61], v[48:49], v[24:25] op_sel_hi:[0,1]
	v_pk_mul_f32 v[62:63], v[48:49], v[26:27] op_sel_hi:[0,1]
	v_add_f32_dpp v58, v58, v58 quad_perm:[1,0,3,2] row_mask:0xf bank_mask:0xf bound_ctrl:1
	ds_read_b128 v[24:27], v76 offset:18944
	v_add_f32_e32 v67, v64, v65
	v_add_f32_dpp v58, v58, v58 quad_perm:[2,3,0,1] row_mask:0xf bank_mask:0xf bound_ctrl:1
	v_pk_fma_f32 v[60:61], v[4:5], v[8:9], v[60:61]
	v_pk_fma_f32 v[62:63], v[6:7], v[10:11], v[62:63]
	v_add_f32_dpp v71, v66, v66 row_mirror row_mask:0xf bank_mask:0x3
	v_add_f32_dpp v58, v58, v58 row_half_mirror row_mask:0xf bank_mask:0xf bound_ctrl:1
	ds_read_b128 v[8:11], v76 offset:2560
	v_add_f32_dpp v71, v67, v67 row_mirror row_mask:0xf bank_mask:0xc
	v_add_f32_dpp v58, v58, v58 row_mirror row_mask:0xf bank_mask:0xf bound_ctrl:1
	v_pk_fma_f32 v[4:5], v[58:59], v[16:17], v[60:61] op_sel_hi:[0,1,1]
	v_pk_fma_f32 v[6:7], v[58:59], v[18:19], v[62:63] op_sel_hi:[0,1,1]
	ds_read_b128 v[16:19], v76 offset:10752
	s_waitcnt lgkmcnt(5)
; DI void scan_task(const Params& p, int l, int isP, int b, int h, int rg, char* smem, const bool dry) {
;     ...
; #pragma unroll
;     for (int s = 0; s < 32; s++) {
;       f32x4 w4n = w4, a4n = a4, b4n = b4;
;       uint2 urn = ur, ukn = uk;
;       float vn = v;
;       if (s < 31) {
;         w4n = *(const f32x4*)(fw + (s + 1) * 64);
;         a4n = *(const f32x4*)(fa + (s + 1) * 64);
;         b4n = *(const f32x4*)(fb + (s + 1) * 64);
;         urn = *(const uint2*)(pr + (s + 1) * 128);
;         ukn = *(const uint2*)(pk + (s + 1) * 128);
;         vn = vb[(s + 1) * 16];
;       }
;       __builtin_amdgcn_sched_barrier(0);
;       const f32x2 klo = {__uint_as_float(uk.x << 16), __uint_as_float(uk.x & 0xFFFF0000u)};
;       const f32x2 khi = {__uint_as_float(uk.y << 16), __uint_as_float(uk.y & 0xFFFF0000u)};
;       const f32x2 rlo = {__uint_as_float(ur.x << 16), __uint_as_float(ur.x & 0xFFFF0000u)};
;       const f32x2 rhi = {__uint_as_float(ur.y << 16), __uint_as_float(ur.y & 0xFFFF0000u)};
;       const f32x2 vv = {v, v};
;       const f32x2 t = Sa * a4.lo + Sb * a4.hi;
;       const f32x2 na = Sa * w4.lo + vv * klo;
;       const f32x2 nb = Sb * w4.hi + vv * khi;
;       float sa = t.x + t.y;
;       float yp = yprev;
;       rowsum16x2(sa, yp);
;       if (s >= 1 && s <= 16) ykeep0 = (jq == s - 1) ? yp : ykeep0;
;       if (s >= 17) ykeep1 = (jq == s - 17) ? yp : ykeep1;
;       const f32x2 sv = {sa, sa};
;       Sa = na + sv * b4.lo;
;       Sb = nb + sv * b4.hi;
;       const f32x2 yy = Sa * rlo + Sb * rhi;
;       yprev = yy.x + yy.y;
;       w4 = w4n; a4 = a4n; b4 = b4n; ur = urn; uk = ukn; v = vn;
;     }
	v_pk_mul_f32 v[56:57], v[4:5], v[32:33]
	v_pk_mul_f32 v[64:65], v[4:5], v[20:21]
	v_pk_fma_f32 v[56:57], v[6:7], v[34:35], v[56:57]
	ds_read_b128 v[32:35], v76 offset:6912
	v_pk_fma_f32 v[64:65], v[6:7], v[22:23], v[64:65]
	ds_read_b128 v[20:23], v76 offset:14848
	v_add_f32_e32 v58, v56, v57
	v_pk_mul_f32 v[60:61], v[48:49], v[44:45] op_sel:[1,0] op_sel_hi:[1,1]
	v_pk_mul_f32 v[62:63], v[48:49], v[46:47] op_sel:[1,0] op_sel_hi:[1,1]
	v_add_f32_dpp v58, v58, v58 quad_perm:[1,0,3,2] row_mask:0xf bank_mask:0xf bound_ctrl:1
	ds_read_b128 v[44:47], v76 offset:19200
	v_add_f32_e32 v66, v64, v65
	ds_read_b128 v[52:55], v77 offset:20528
	v_add_f32_dpp v58, v58, v58 quad_perm:[2,3,0,1] row_mask:0xf bank_mask:0xf bound_ctrl:1
	v_pk_fma_f32 v[60:61], v[4:5], v[28:29], v[60:61]
	v_pk_fma_f32 v[62:63], v[6:7], v[30:31], v[62:63]
	v_add_f32_dpp v70, v70, v70 row_half_mirror row_mask:0xf bank_mask:0x5
	v_add_f32_dpp v58, v58, v58 row_half_mirror row_mask:0xf bank_mask:0xf bound_ctrl:1
	ds_read_b128 v[28:31], v76 offset:2816
	v_add_f32_dpp v70, v71, v71 row_half_mirror row_mask:0xf bank_mask:0xa
	v_add_f32_dpp v58, v58, v58 row_mirror row_mask:0xf bank_mask:0xf bound_ctrl:1
	v_pk_fma_f32 v[4:5], v[58:59], v[36:37], v[60:61] op_sel_hi:[0,1,1]
	v_pk_fma_f32 v[6:7], v[58:59], v[38:39], v[62:63] op_sel_hi:[0,1,1]
	ds_read_b128 v[36:39], v76 offset:11008
	s_waitcnt lgkmcnt(6)
	v_pk_mul_f32 v[56:57], v[4:5], v[12:13]
	v_pk_mul_f32 v[64:65], v[4:5], v[40:41]
	v_pk_fma_f32 v[56:57], v[6:7], v[14:15], v[56:57]
	ds_read_b128 v[12:15], v76 offset:7168
	v_pk_fma_f32 v[64:65], v[6:7], v[42:43], v[64:65]
	ds_read_b128 v[40:43], v76 offset:15104
	v_add_f32_e32 v58, v56, v57
	v_pk_mul_f32 v[60:61], v[50:51], v[24:25] op_sel_hi:[0,1]
	v_pk_mul_f32 v[62:63], v[50:51], v[26:27] op_sel_hi:[0,1]
	v_add_f32_dpp v58, v58, v58 quad_perm:[1,0,3,2] row_mask:0xf bank_mask:0xf bound_ctrl:1
	ds_read_b128 v[24:27], v76 offset:19456
	v_add_f32_e32 v67, v64, v65
	v_add_f32_dpp v58, v58, v58 quad_perm:[2,3,0,1] row_mask:0xf bank_mask:0xf bound_ctrl:1
	v_pk_fma_f32 v[60:61], v[4:5], v[8:9], v[60:61]
	v_pk_fma_f32 v[62:63], v[6:7], v[10:11], v[62:63]
	v_add_f32_dpp v72, v66, v66 row_mirror row_mask:0xf bank_mask:0x3
	v_add_f32_dpp v58, v58, v58 row_half_mirror row_mask:0xf bank_mask:0xf bound_ctrl:1
	ds_read_b128 v[8:11], v76 offset:3072
	v_add_f32_dpp v72, v67, v67 row_mirror row_mask:0xf bank_mask:0xc
	v_add_f32_dpp v58, v58, v58 row_mirror row_mask:0xf bank_mask:0xf bound_ctrl:1
	v_pk_fma_f32 v[4:5], v[58:59], v[16:17], v[60:61] op_sel_hi:[0,1,1]
	v_pk_fma_f32 v[6:7], v[58:59], v[18:19], v[62:63] op_sel_hi:[0,1,1]
	ds_read_b128 v[16:19], v76 offset:11264
	s_waitcnt lgkmcnt(5)
	v_pk_mul_f32 v[56:57], v[4:5], v[32:33]
	v_pk_mul_f32 v[64:65], v[4:5], v[20:21]
	v_pk_fma_f32 v[56:57], v[6:7], v[34:35], v[56:57]
	ds_read_b128 v[32:35], v76 offset:7424
	v_pk_fma_f32 v[64:65], v[6:7], v[22:23], v[64:65]
	ds_read_b128 v[20:23], v76 offset:15360
	v_add_f32_e32 v58, v56, v57
	v_pk_mul_f32 v[60:61], v[50:51], v[44:45] op_sel:[1,0] op_sel_hi:[1,1]
	v_pk_mul_f32 v[62:63], v[50:51], v[46:47] op_sel:[1,0] op_sel_hi:[1,1]
	v_add_f32_dpp v58, v58, v58 quad_perm:[1,0,3,2] row_mask:0xf bank_mask:0xf bound_ctrl:1
	ds_read_b128 v[44:47], v76 offset:19712
	v_add_f32_e32 v66, v64, v65
	v_add_f32_dpp v58, v58, v58 quad_perm:[2,3,0,1] row_mask:0xf bank_mask:0xf bound_ctrl:1
	v_pk_fma_f32 v[60:61], v[4:5], v[28:29], v[60:61]
	v_pk_fma_f32 v[62:63], v[6:7], v[30:31], v[62:63]
	v_add_f32_dpp v58, v58, v58 row_half_mirror row_mask:0xf bank_mask:0xf bound_ctrl:1
	ds_read_b128 v[28:31], v76 offset:3328
	s_nop 0
	v_add_f32_dpp v58, v58, v58 row_mirror row_mask:0xf bank_mask:0xf bound_ctrl:1
	v_pk_fma_f32 v[4:5], v[58:59], v[36:37], v[60:61] op_sel_hi:[0,1,1]
	v_pk_fma_f32 v[6:7], v[58:59], v[38:39], v[62:63] op_sel_hi:[0,1,1]
	ds_read_b128 v[36:39], v76 offset:11520
	s_waitcnt lgkmcnt(5)
	v_pk_mul_f32 v[56:57], v[4:5], v[12:13]
	v_pk_mul_f32 v[64:65], v[4:5], v[40:41]
	v_pk_fma_f32 v[56:57], v[6:7], v[14:15], v[56:57]
	ds_read_b128 v[12:15], v76 offset:7680
	v_pk_fma_f32 v[64:65], v[6:7], v[42:43], v[64:65]
	ds_read_b128 v[40:43], v76 offset:15616
	v_add_f32_e32 v58, v56, v57
	v_pk_mul_f32 v[60:61], v[52:53], v[24:25] op_sel_hi:[0,1]
	v_pk_mul_f32 v[62:63], v[52:53], v[26:27] op_sel_hi:[0,1]
	v_add_f32_dpp v58, v58, v58 quad_perm:[1,0,3,2] row_mask:0xf bank_mask:0xf bound_ctrl:1
	ds_read_b128 v[24:27], v76 offset:19968
	v_add_f32_e32 v67, v64, v65
	v_add_f32_dpp v58, v58, v58 quad_perm:[2,3,0,1] row_mask:0xf bank_mask:0xf bound_ctrl:1
	v_pk_fma_f32 v[60:61], v[4:5], v[8:9], v[60:61]
	v_pk_fma_f32 v[62:63], v[6:7], v[10:11], v[62:63]
	v_add_f32_dpp v73, v66, v66 row_mirror row_mask:0xf bank_mask:0x3
	v_add_f32_dpp v58, v58, v58 row_half_mirror row_mask:0xf bank_mask:0xf bound_ctrl:1
	ds_read_b128 v[8:11], v76 offset:3584
	v_add_f32_dpp v73, v67, v67 row_mirror row_mask:0xf bank_mask:0xc
	v_add_f32_dpp v58, v58, v58 row_mirror row_mask:0xf bank_mask:0xf bound_ctrl:1
	v_pk_fma_f32 v[4:5], v[58:59], v[16:17], v[60:61] op_sel_hi:[0,1,1]
	v_pk_fma_f32 v[6:7], v[58:59], v[18:19], v[62:63] op_sel_hi:[0,1,1]
	ds_read_b128 v[16:19], v76 offset:11776
	s_waitcnt lgkmcnt(5)
; DI void scan_task(const Params& p, int l, int isP, int b, int h, int rg, char* smem, const bool dry) {
;     ...
;   auto sstore = [&](int bi) {
;     char* bb = smem + bi * BUFB;
;     *(float4*)(bb + (ds * 64 + dj * 4) * 4) = rd0;
;     *(float4*)(bb + ((16 + ds) * 64 + dj * 4) * 4) = rd1;
;     {
;       CVT8(qa, alo, ahi)
;       float* d = (float*)(bb + 8192) + lst * 64 + lch * 8;
;       *(float4*)d = alo; *(float4*)(d + 4) = ahi;
;     }
;     {
;       CVT8(qb, blo, bhi)
;       float* d = (float*)(bb + 16384) + lst * 64 + lch * 8;
;       *(float4*)d = blo; *(float4*)(d + 4) = bhi;
;     }
;     *(uint4*)(bb + 24576 + (lst * 64 + lch * 8) * 2) = qr;
;     *(uint4*)(bb + 28672 + (lst * 64 + lch * 8) * 2) = qk;
;     if (tid < 64) {
;       const int s = tid >> 1, half = tid & 1;
;       CVT8(rv, vlo, vhi)
;       float* d = (float*)(bb + 32768) + s * 16 + half * 8;
;       *(float4*)d = vlo; *(float4*)(d + 4) = vhi;
;     }
;   };
;     ...
;       const f32x2 t = Sa * a4.lo + Sb * a4.hi;
;       const f32x2 na = Sa * w4.lo + vv * klo;
;       const f32x2 nb = Sb * w4.hi + vv * khi;
;       float sa = t.x + t.y;
;       float yp = yprev;
;       rowsum16x2(sa, yp);
;       if (s >= 1 && s <= 16) ykeep0 = (jq == s - 1) ? yp : ykeep0;
;       if (s >= 17) ykeep1 = (jq == s - 17) ? yp : ykeep1;
;       const f32x2 sv = {sa, sa};
;       Sa = na + sv * b4.lo;
;       Sb = nb + sv * b4.hi;
;       const f32x2 yy = Sa * rlo + Sb * rhi;
;       yprev = yy.x + yy.y;
;       w4 = w4n; a4 = a4n; b4 = b4n; ur = urn; uk = ukn; v = vn;
;     }
;     {
;       const float yl = rowsum16(yprev);
;       ykeep1 = (jq == 15) ? yl : ykeep1;
;     }
;     if (!dry) { yo[0] = ykeep0; yo[(size_t)16 * 512] = ykeep1; }
;     if (more) sstore((c + 1) & 1);
;     __syncthreads();
	v_pk_mul_f32 v[56:57], v[4:5], v[32:33]
	v_pk_mul_f32 v[64:65], v[4:5], v[20:21]
	v_pk_fma_f32 v[56:57], v[6:7], v[34:35], v[56:57]
	ds_read_b128 v[32:35], v76 offset:7936
	v_pk_fma_f32 v[64:65], v[6:7], v[22:23], v[64:65]
	ds_read_b128 v[20:23], v76 offset:15872
	v_add_f32_e32 v58, v56, v57
	v_pk_mul_f32 v[60:61], v[52:53], v[44:45] op_sel:[1,0] op_sel_hi:[1,1]
	v_pk_mul_f32 v[62:63], v[52:53], v[46:47] op_sel:[1,0] op_sel_hi:[1,1]
	v_add_f32_dpp v58, v58, v58 quad_perm:[1,0,3,2] row_mask:0xf bank_mask:0xf bound_ctrl:1
	ds_read_b128 v[44:47], v76 offset:20224
	v_add_f32_e32 v66, v64, v65
	v_add_f32_dpp v58, v58, v58 quad_perm:[2,3,0,1] row_mask:0xf bank_mask:0xf bound_ctrl:1
	v_pk_fma_f32 v[60:61], v[4:5], v[28:29], v[60:61]
	v_pk_fma_f32 v[62:63], v[6:7], v[30:31], v[62:63]
	v_add_f32_dpp v72, v72, v72 row_half_mirror row_mask:0xf bank_mask:0x5
	v_add_f32_dpp v58, v58, v58 row_half_mirror row_mask:0xf bank_mask:0xf bound_ctrl:1
	ds_read_b128 v[28:31], v76 offset:3840
	v_add_f32_dpp v72, v73, v73 row_half_mirror row_mask:0xf bank_mask:0xa
	v_add_f32_dpp v58, v58, v58 row_mirror row_mask:0xf bank_mask:0xf bound_ctrl:1
	v_pk_fma_f32 v[4:5], v[58:59], v[36:37], v[60:61] op_sel_hi:[0,1,1]
	v_pk_fma_f32 v[6:7], v[58:59], v[38:39], v[62:63] op_sel_hi:[0,1,1]
	ds_read_b128 v[36:39], v76 offset:12032
	s_waitcnt lgkmcnt(5)
	v_pk_mul_f32 v[56:57], v[4:5], v[12:13]
	v_pk_mul_f32 v[64:65], v[4:5], v[40:41]
	v_pk_fma_f32 v[56:57], v[6:7], v[14:15], v[56:57]
	v_pk_fma_f32 v[64:65], v[6:7], v[42:43], v[64:65]
	ds_read_b128 v[40:43], v76 offset:16128
	v_add_f32_e32 v58, v56, v57
	v_pk_mul_f32 v[60:61], v[54:55], v[24:25] op_sel_hi:[0,1]
	v_pk_mul_f32 v[62:63], v[54:55], v[26:27] op_sel_hi:[0,1]
	v_add_f32_dpp v58, v58, v58 quad_perm:[1,0,3,2] row_mask:0xf bank_mask:0xf bound_ctrl:1
	v_add_f32_e32 v67, v64, v65
	s_nop 0
	v_add_f32_dpp v58, v58, v58 quad_perm:[2,3,0,1] row_mask:0xf bank_mask:0xf bound_ctrl:1
	v_pk_fma_f32 v[60:61], v[4:5], v[8:9], v[60:61]
	v_pk_fma_f32 v[62:63], v[6:7], v[10:11], v[62:63]
	v_add_f32_dpp v74, v66, v66 row_mirror row_mask:0xf bank_mask:0x3
	v_add_f32_dpp v58, v58, v58 row_half_mirror row_mask:0xf bank_mask:0xf bound_ctrl:1
	s_nop 0
	v_add_f32_dpp v74, v67, v67 row_mirror row_mask:0xf bank_mask:0xc
	v_add_f32_dpp v58, v58, v58 row_mirror row_mask:0xf bank_mask:0xf bound_ctrl:1
	v_pk_fma_f32 v[4:5], v[58:59], v[16:17], v[60:61] op_sel_hi:[0,1,1]
	v_pk_fma_f32 v[6:7], v[58:59], v[18:19], v[62:63] op_sel_hi:[0,1,1]
	s_waitcnt lgkmcnt(1)
	v_pk_mul_f32 v[56:57], v[4:5], v[32:33]
	v_pk_mul_f32 v[64:65], v[4:5], v[20:21]
	v_pk_fma_f32 v[56:57], v[6:7], v[34:35], v[56:57]
	v_pk_fma_f32 v[64:65], v[6:7], v[22:23], v[64:65]
	v_add_f32_e32 v58, v56, v57
	v_pk_mul_f32 v[60:61], v[54:55], v[44:45] op_sel:[1,0] op_sel_hi:[1,1]
	v_pk_mul_f32 v[62:63], v[54:55], v[46:47] op_sel:[1,0] op_sel_hi:[1,1]
	v_add_f32_dpp v58, v58, v58 quad_perm:[1,0,3,2] row_mask:0xf bank_mask:0xf bound_ctrl:1
	v_add_f32_e32 v66, v64, v65
	s_nop 0
	v_add_f32_dpp v58, v58, v58 quad_perm:[2,3,0,1] row_mask:0xf bank_mask:0xf bound_ctrl:1
	v_pk_fma_f32 v[60:61], v[4:5], v[28:29], v[60:61]
	v_pk_fma_f32 v[62:63], v[6:7], v[30:31], v[62:63]
	v_add_f32_dpp v58, v58, v58 row_half_mirror row_mask:0xf bank_mask:0xf bound_ctrl:1
	s_nop 1
	v_add_f32_dpp v58, v58, v58 row_mirror row_mask:0xf bank_mask:0xf bound_ctrl:1
	v_pk_fma_f32 v[4:5], v[58:59], v[36:37], v[60:61] op_sel_hi:[0,1,1]
	v_pk_fma_f32 v[6:7], v[58:59], v[38:39], v[62:63] op_sel_hi:[0,1,1]
	s_waitcnt lgkmcnt(0)
	v_pk_mul_f32 v[64:65], v[4:5], v[40:41]
	v_pk_fma_f32 v[64:65], v[6:7], v[42:43], v[64:65]
	v_add_f32_e32 v67, v64, v65
	s_cmp_lg_u32 s22, 0
	s_cbranch_scc1 .Lscan_w6A
	s_waitcnt vmcnt(0)
	s_branch .Lscan_wdA
.Lscan_w6A:
	s_waitcnt vmcnt(6)
.Lscan_wdA:
	ds_write_b128 v78, v[100:103] offset:21504
	v_lshlrev_b32_e32 v8, 16, v108
	v_and_b32_e32 v9, 0xffff0000, v108
	v_lshlrev_b32_e32 v10, 16, v109
	v_and_b32_e32 v11, 0xffff0000, v109
	ds_write_b128 v78, v[8:11] offset:25600
	v_lshlrev_b32_e32 v12, 16, v98
	v_and_b32_e32 v13, 0xffff0000, v98
	v_lshlrev_b32_e32 v14, 16, v99
	v_and_b32_e32 v15, 0xffff0000, v99
	ds_write_b128 v78, v[12:15] offset:29696
	v_lshlrev_b32_e32 v16, 16, v104
	v_and_b32_e32 v17, 0xffff0000, v104
	v_lshlrev_b32_e32 v18, 16, v105
	v_and_b32_e32 v19, 0xffff0000, v105
	ds_write_b128 v78, v[16:19] offset:33792
	v_lshlrev_b32_e32 v20, 16, v106
	v_and_b32_e32 v21, 0xffff0000, v106
	v_lshlrev_b32_e32 v22, 16, v107
	v_and_b32_e32 v23, 0xffff0000, v107
	ds_write_b128 v78, v[20:23] offset:37888
	v_lshlrev_b32_e32 v24, 16, v97
	ds_write_b32 v79, v24 offset:41984
	s_waitcnt lgkmcnt(0)
	s_barrier
	ds_read_b128 v[12:15], v76 offset:25600
	ds_read_b128 v[24:27], v76 offset:37888
	ds_read_b128 v[48:51], v77 offset:41984
	ds_read_b128 v[8:11], v76 offset:21504
	ds_read_b128 v[16:19], v76 offset:29696
	ds_read_b128 v[20:23], v76 offset:33792
	ds_read_b128 v[32:35], v76 offset:25856
	ds_read_b128 v[44:47], v76 offset:38144
	ds_read_b128 v[28:31], v76 offset:21760
	ds_read_b128 v[36:39], v76 offset:29952
	ds_read_b128 v[40:43], v76 offset:34048
	v_add_f32_dpp v75, v66, v66 row_mirror row_mask:0xf bank_mask:0x3
	v_add_f32_dpp v74, v74, v74 row_half_mirror row_mask:0xf bank_mask:0x5
	v_add_f32_dpp v68, v68, v68 quad_perm:[1,0,3,2] row_mask:0xf bank_mask:0xf
	v_add_f32_dpp v75, v67, v67 row_mirror row_mask:0xf bank_mask:0xc
	v_add_f32_dpp v70, v70, v70 quad_perm:[1,0,3,2] row_mask:0xf bank_mask:0xf
	v_add_f32_dpp v72, v72, v72 quad_perm:[1,0,3,2] row_mask:0xf bank_mask:0xf
	v_add_f32_dpp v74, v75, v75 row_half_mirror row_mask:0xf bank_mask:0xa
	v_add_f32_dpp v68, v68, v68 quad_perm:[2,3,0,1] row_mask:0xf bank_mask:0xf
	v_add_f32_dpp v70, v70, v70 quad_perm:[2,3,0,1] row_mask:0xf bank_mask:0xf
	v_add_f32_dpp v74, v74, v74 quad_perm:[1,0,3,2] row_mask:0xf bank_mask:0xf
	v_add_f32_dpp v72, v72, v72 quad_perm:[2,3,0,1] row_mask:0xf bank_mask:0xf
	v_cndmask_b32_e64 v68, v68, v70, s[18:19]
	v_add_f32_dpp v74, v74, v74 quad_perm:[2,3,0,1] row_mask:0xf bank_mask:0xf
	v_cndmask_b32_e64 v72, v72, v74, s[18:19]
	v_cndmask_b32_e64 v68, v68, v72, s[20:21]
	global_store_dword v83, v68, s[14:15]
	s_add_u32 s14, s14, 0x8000
	s_addc_u32 s15, s15, 0
; DI void scan_task(const Params& p, int l, int isP, int b, int h, int rg, char* smem, const bool dry) {
;     ...
;   for (int c = 0; c < nch; c++) {
;     const bool more = c + 1 < nch;
;     if (more) gload(c + 1);
;     const char* bb = smem + (c & 1) * BUFB;
;     const float* fw = (const float*)bb + jq * 4;
;     const float* fa = (const float*)(bb + 8192) + jq * 4;
;     const float* fb = (const float*)(bb + 16384) + jq * 4;
;     const char* pr = bb + 24576 + jq * 8;
;     const char* pk = bb + 28672 + jq * 8;
;     const float* vb = (const float*)(bb + 32768) + wave * 4 + g4;
;     float* yo = p.yscan + (size_t)(tokbase + c * 32 + jq) * 512 + h * 64 + i;
;     float ykeep0 = 0.f, ykeep1 = 0.f, yprev = 0.f;
;     f32x4 w4 = *(const f32x4*)fw, a4 = *(const f32x4*)fa, b4 = *(const f32x4*)fb;
;     uint2 ur = *(const uint2*)pr, uk = *(const uint2*)pk;
;     float v = vb[0];
; #pragma unroll
;     for (int s = 0; s < 32; s++) {
;       f32x4 w4n = w4, a4n = a4, b4n = b4;
;       uint2 urn = ur, ukn = uk;
;       float vn = v;
;       if (s < 31) {
;         w4n = *(const f32x4*)(fw + (s + 1) * 64);
;         a4n = *(const f32x4*)(fa + (s + 1) * 64);
;         b4n = *(const f32x4*)(fb + (s + 1) * 64);
;         urn = *(const uint2*)(pr + (s + 1) * 128);
;         ukn = *(const uint2*)(pk + (s + 1) * 128);
;         vn = vb[(s + 1) * 16];
;       }
;       __builtin_amdgcn_sched_barrier(0);
;       const f32x2 klo = {__uint_as_float(uk.x << 16), __uint_as_float(uk.x & 0xFFFF0000u)};
;       const f32x2 khi = {__uint_as_float(uk.y << 16), __uint_as_float(uk.y & 0xFFFF0000u)};
;       const f32x2 rlo = {__uint_as_float(ur.x << 16), __uint_as_float(ur.x & 0xFFFF0000u)};
;       const f32x2 rhi = {__uint_as_float(ur.y << 16), __uint_as_float(ur.y & 0xFFFF0000u)};
;       const f32x2 vv = {v, v};
;       const f32x2 t = Sa * a4.lo + Sb * a4.hi;
;       const f32x2 na = Sa * w4.lo + vv * klo;
;       const f32x2 nb = Sb * w4.hi + vv * khi;
;       float sa = t.x + t.y;
;       float yp = yprev;
;       rowsum16x2(sa, yp);
;       if (s >= 1 && s <= 16) ykeep0 = (jq == s - 1) ? yp : ykeep0;
;       if (s >= 17) ykeep1 = (jq == s - 17) ? yp : ykeep1;
;       const f32x2 sv = {sa, sa};
;       Sa = na + sv * b4.lo;
;       Sb = nb + sv * b4.hi;
;       const f32x2 yy = Sa * rlo + Sb * rhi;
;       yprev = yy.x + yy.y;
.Lscan_bodyB:
	s_add_i32 s23, s16, 3
	s_cmp_lt_u32 s23, s17
	s_cselect_b32 s22, 1, 0
	s_cbranch_scc0 .Lscan_noldB
	global_load_dwordx4 v[100:103], v80, s[12:13]
	global_load_dwordx2 v[104:105], v81, s[12:13] offset:-1024
	global_load_dwordx2 v[106:107], v81, s[12:13]
	global_load_dwordx2 v[108:109], v81, s[12:13] offset:2048
	global_load_dwordx2 v[98:99], v81, s[12:13] offset:3072
	global_load_ushort v97, v82, s[12:13]
	s_add_u32 s12, s12, 0x1c000
	s_addc_u32 s13, s13, 0
.Lscan_noldB:
	s_waitcnt lgkmcnt(6)
	v_pk_mul_f32 v[56:57], v[4:5], v[12:13]
	v_pk_fma_f32 v[56:57], v[6:7], v[14:15], v[56:57]
	ds_read_b128 v[12:15], v76 offset:26112
	v_add_f32_e32 v58, v56, v57
	v_pk_mul_f32 v[60:61], v[48:49], v[24:25] op_sel_hi:[0,1]
	v_pk_mul_f32 v[62:63], v[48:49], v[26:27] op_sel_hi:[0,1]
	v_add_f32_dpp v58, v58, v58 quad_perm:[1,0,3,2] row_mask:0xf bank_mask:0xf bound_ctrl:1
	ds_read_b128 v[24:27], v76 offset:38400
	s_nop 0
	v_add_f32_dpp v58, v58, v58 quad_perm:[2,3,0,1] row_mask:0xf bank_mask:0xf bound_ctrl:1
	v_pk_fma_f32 v[60:61], v[4:5], v[8:9], v[60:61]
	v_pk_fma_f32 v[62:63], v[6:7], v[10:11], v[62:63]
	v_add_f32_dpp v58, v58, v58 row_half_mirror row_mask:0xf bank_mask:0xf bound_ctrl:1
	ds_read_b128 v[8:11], v76 offset:22016
	s_nop 0
	v_add_f32_dpp v58, v58, v58 row_mirror row_mask:0xf bank_mask:0xf bound_ctrl:1
	v_pk_fma_f32 v[4:5], v[58:59], v[16:17], v[60:61] op_sel_hi:[0,1,1]
	v_pk_fma_f32 v[6:7], v[58:59], v[18:19], v[62:63] op_sel_hi:[0,1,1]
	ds_read_b128 v[16:19], v76 offset:30208
	s_waitcnt lgkmcnt(5)
	v_pk_mul_f32 v[56:57], v[4:5], v[32:33]
	v_pk_mul_f32 v[64:65], v[4:5], v[20:21]
	v_pk_fma_f32 v[56:57], v[6:7], v[34:35], v[56:57]
	ds_read_b128 v[32:35], v76 offset:26368
	v_pk_fma_f32 v[64:65], v[6:7], v[22:23], v[64:65]
	ds_read_b128 v[20:23], v76 offset:34304
	v_add_f32_e32 v58, v56, v57
	v_pk_mul_f32 v[60:61], v[48:49], v[44:45] op_sel:[1,0] op_sel_hi:[1,1]
	v_pk_mul_f32 v[62:63], v[48:49], v[46:47] op_sel:[1,0] op_sel_hi:[1,1]
	v_add_f32_dpp v58, v58, v58 quad_perm:[1,0,3,2] row_mask:0xf bank_mask:0xf bound_ctrl:1
	ds_read_b128 v[44:47], v76 offset:38656
	v_add_f32_e32 v66, v64, v65
	ds_read_b128 v[52:55], v77 offset:42000
	v_add_f32_dpp v58, v58, v58 quad_perm:[2,3,0,1] row_mask:0xf bank_mask:0xf bound_ctrl:1
	v_pk_fma_f32 v[60:61], v[4:5], v[28:29], v[60:61]
	v_pk_fma_f32 v[62:63], v[6:7], v[30:31], v[62:63]
	v_add_f32_dpp v58, v58, v58 row_half_mirror row_mask:0xf bank_mask:0xf bound_ctrl:1
	ds_read_b128 v[28:31], v76 offset:22272
	s_nop 0
	v_add_f32_dpp v58, v58, v58 row_mirror row_mask:0xf bank_mask:0xf bound_ctrl:1
	v_pk_fma_f32 v[4:5], v[58:59], v[36:37], v[60:61] op_sel_hi:[0,1,1]
	v_pk_fma_f32 v[6:7], v[58:59], v[38:39], v[62:63] op_sel_hi:[0,1,1]
	ds_read_b128 v[36:39], v76 offset:30464
	s_waitcnt lgkmcnt(6)
	v_pk_mul_f32 v[56:57], v[4:5], v[12:13]
	v_pk_mul_f32 v[64:65], v[4:5], v[40:41]
	v_pk_fma_f32 v[56:57], v[6:7], v[14:15], v[56:57]
	ds_read_b128 v[12:15], v76 offset:26624
	v_pk_fma_f32 v[64:65], v[6:7], v[42:43], v[64:65]
	ds_read_b128 v[40:43], v76 offset:34560
	v_add_f32_e32 v58, v56, v57
	v_pk_mul_f32 v[60:61], v[50:51], v[24:25] op_sel_hi:[0,1]
	v_pk_mul_f32 v[62:63], v[50:51], v[26:27] op_sel_hi:[0,1]
	v_add_f32_dpp v58, v58, v58 quad_perm:[1,0,3,2] row_mask:0xf bank_mask:0xf bound_ctrl:1
	ds_read_b128 v[24:27], v76 offset:38912
	v_add_f32_e32 v67, v64, v65
	v_add_f32_dpp v58, v58, v58 quad_perm:[2,3,0,1] row_mask:0xf bank_mask:0xf bound_ctrl:1
	v_pk_fma_f32 v[60:61], v[4:5], v[8:9], v[60:61]
	v_pk_fma_f32 v[62:63], v[6:7], v[10:11], v[62:63]
	v_add_f32_dpp v68, v66, v66 row_mirror row_mask:0xf bank_mask:0x3
	v_add_f32_dpp v58, v58, v58 row_half_mirror row_mask:0xf bank_mask:0xf bound_ctrl:1
	ds_read_b128 v[8:11], v76 offset:22528
	v_add_f32_dpp v68, v67, v67 row_mirror row_mask:0xf bank_mask:0xc
	v_add_f32_dpp v58, v58, v58 row_mirror row_mask:0xf bank_mask:0xf bound_ctrl:1
	v_pk_fma_f32 v[4:5], v[58:59], v[16:17], v[60:61] op_sel_hi:[0,1,1]
	v_pk_fma_f32 v[6:7], v[58:59], v[18:19], v[62:63] op_sel_hi:[0,1,1]
	ds_read_b128 v[16:19], v76 offset:30720
	s_waitcnt lgkmcnt(5)
	v_pk_mul_f32 v[56:57], v[4:5], v[32:33]
	v_pk_mul_f32 v[64:65], v[4:5], v[20:21]
	v_pk_fma_f32 v[56:57], v[6:7], v[34:35], v[56:57]
	ds_read_b128 v[32:35], v76 offset:26880
	v_pk_fma_f32 v[64:65], v[6:7], v[22:23], v[64:65]
	ds_read_b128 v[20:23], v76 offset:34816
	v_add_f32_e32 v58, v56, v57
	v_pk_mul_f32 v[60:61], v[50:51], v[44:45] op_sel:[1,0] op_sel_hi:[1,1]
	v_pk_mul_f32 v[62:63], v[50:51], v[46:47] op_sel:[1,0] op_sel_hi:[1,1]
	v_add_f32_dpp v58, v58, v58 quad_perm:[1,0,3,2] row_mask:0xf bank_mask:0xf bound_ctrl:1
	ds_read_b128 v[44:47], v76 offset:39168
	v_add_f32_e32 v66, v64, v65
	v_add_f32_dpp v58, v58, v58 quad_perm:[2,3,0,1] row_mask:0xf bank_mask:0xf bound_ctrl:1
	v_pk_fma_f32 v[60:61], v[4:5], v[28:29], v[60:61]
	v_pk_fma_f32 v[62:63], v[6:7], v[30:31], v[62:63]
	v_add_f32_dpp v58, v58, v58 row_half_mirror row_mask:0xf bank_mask:0xf bound_ctrl:1
	ds_read_b128 v[28:31], v76 offset:22784
	s_nop 0
	v_add_f32_dpp v58, v58, v58 row_mirror row_mask:0xf bank_mask:0xf bound_ctrl:1
	v_pk_fma_f32 v[4:5], v[58:59], v[36:37], v[60:61] op_sel_hi:[0,1,1]
	v_pk_fma_f32 v[6:7], v[58:59], v[38:39], v[62:63] op_sel_hi:[0,1,1]
	ds_read_b128 v[36:39], v76 offset:30976
	s_waitcnt lgkmcnt(5)
; DI void scan_task(const Params& p, int l, int isP, int b, int h, int rg, char* smem, const bool dry) {
;     ...
; #pragma unroll
;     for (int s = 0; s < 32; s++) {
;       f32x4 w4n = w4, a4n = a4, b4n = b4;
;       uint2 urn = ur, ukn = uk;
;       float vn = v;
;       if (s < 31) {
;         w4n = *(const f32x4*)(fw + (s + 1) * 64);
;         a4n = *(const f32x4*)(fa + (s + 1) * 64);
;         b4n = *(const f32x4*)(fb + (s + 1) * 64);
;         urn = *(const uint2*)(pr + (s + 1) * 128);
;         ukn = *(const uint2*)(pk + (s + 1) * 128);
;         vn = vb[(s + 1) * 16];
;       }
;       __builtin_amdgcn_sched_barrier(0);
;       const f32x2 klo = {__uint_as_float(uk.x << 16), __uint_as_float(uk.x & 0xFFFF0000u)};
;       const f32x2 khi = {__uint_as_float(uk.y << 16), __uint_as_float(uk.y & 0xFFFF0000u)};
;       const f32x2 rlo = {__uint_as_float(ur.x << 16), __uint_as_float(ur.x & 0xFFFF0000u)};
;       const f32x2 rhi = {__uint_as_float(ur.y << 16), __uint_as_float(ur.y & 0xFFFF0000u)};
;       const f32x2 vv = {v, v};
;       const f32x2 t = Sa * a4.lo + Sb * a4.hi;
;       const f32x2 na = Sa * w4.lo + vv * klo;
;       const f32x2 nb = Sb * w4.hi + vv * khi;
;       float sa = t.x + t.y;
;       float yp = yprev;
;       rowsum16x2(sa, yp);
;       if (s >= 1 && s <= 16) ykeep0 = (jq == s - 1) ? yp : ykeep0;
;       if (s >= 17) ykeep1 = (jq == s - 17) ? yp : ykeep1;
;       const f32x2 sv = {sa, sa};
;       Sa = na + sv * b4.lo;
;       Sb = nb + sv * b4.hi;
;       const f32x2 yy = Sa * rlo + Sb * rhi;
;       yprev = yy.x + yy.y;
;       w4 = w4n; a4 = a4n; b4 = b4n; ur = urn; uk = ukn; v = vn;
;     }
	v_pk_mul_f32 v[56:57], v[4:5], v[12:13]
	v_pk_mul_f32 v[64:65], v[4:5], v[40:41]
	v_pk_fma_f32 v[56:57], v[6:7], v[14:15], v[56:57]
	ds_read_b128 v[12:15], v76 offset:27136
	v_pk_fma_f32 v[64:65], v[6:7], v[42:43], v[64:65]
	ds_read_b128 v[40:43], v76 offset:35072
	v_add_f32_e32 v58, v56, v57
	v_pk_mul_f32 v[60:61], v[52:53], v[24:25] op_sel_hi:[0,1]
	v_pk_mul_f32 v[62:63], v[52:53], v[26:27] op_sel_hi:[0,1]
	v_add_f32_dpp v58, v58, v58 quad_perm:[1,0,3,2] row_mask:0xf bank_mask:0xf bound_ctrl:1
	ds_read_b128 v[24:27], v76 offset:39424
	v_add_f32_e32 v67, v64, v65
	v_add_f32_dpp v58, v58, v58 quad_perm:[2,3,0,1] row_mask:0xf bank_mask:0xf bound_ctrl:1
	v_pk_fma_f32 v[60:61], v[4:5], v[8:9], v[60:61]
	v_pk_fma_f32 v[62:63], v[6:7], v[10:11], v[62:63]
	v_add_f32_dpp v69, v66, v66 row_mirror row_mask:0xf bank_mask:0x3
	v_add_f32_dpp v58, v58, v58 row_half_mirror row_mask:0xf bank_mask:0xf bound_ctrl:1
	ds_read_b128 v[8:11], v76 offset:23040
	v_add_f32_dpp v69, v67, v67 row_mirror row_mask:0xf bank_mask:0xc
	v_add_f32_dpp v58, v58, v58 row_mirror row_mask:0xf bank_mask:0xf bound_ctrl:1
	v_pk_fma_f32 v[4:5], v[58:59], v[16:17], v[60:61] op_sel_hi:[0,1,1]
	v_pk_fma_f32 v[6:7], v[58:59], v[18:19], v[62:63] op_sel_hi:[0,1,1]
	ds_read_b128 v[16:19], v76 offset:31232
	s_waitcnt lgkmcnt(5)
	v_pk_mul_f32 v[56:57], v[4:5], v[32:33]
	v_pk_mul_f32 v[64:65], v[4:5], v[20:21]
	v_pk_fma_f32 v[56:57], v[6:7], v[34:35], v[56:57]
	ds_read_b128 v[32:35], v76 offset:27392
	v_pk_fma_f32 v[64:65], v[6:7], v[22:23], v[64:65]
	ds_read_b128 v[20:23], v76 offset:35328
	v_add_f32_e32 v58, v56, v57
	v_pk_mul_f32 v[60:61], v[52:53], v[44:45] op_sel:[1,0] op_sel_hi:[1,1]
	v_pk_mul_f32 v[62:63], v[52:53], v[46:47] op_sel:[1,0] op_sel_hi:[1,1]
	v_add_f32_dpp v58, v58, v58 quad_perm:[1,0,3,2] row_mask:0xf bank_mask:0xf bound_ctrl:1
	ds_read_b128 v[44:47], v76 offset:39680
	v_add_f32_e32 v66, v64, v65
	ds_read_b128 v[48:51], v77 offset:42016
	v_add_f32_dpp v58, v58, v58 quad_perm:[2,3,0,1] row_mask:0xf bank_mask:0xf bound_ctrl:1
	v_pk_fma_f32 v[60:61], v[4:5], v[28:29], v[60:61]
	v_pk_fma_f32 v[62:63], v[6:7], v[30:31], v[62:63]
	v_add_f32_dpp v68, v68, v68 row_half_mirror row_mask:0xf bank_mask:0x5
	v_add_f32_dpp v58, v58, v58 row_half_mirror row_mask:0xf bank_mask:0xf bound_ctrl:1
	ds_read_b128 v[28:31], v76 offset:23296
	v_add_f32_dpp v68, v69, v69 row_half_mirror row_mask:0xf bank_mask:0xa
	v_add_f32_dpp v58, v58, v58 row_mirror row_mask:0xf bank_mask:0xf bound_ctrl:1
	v_pk_fma_f32 v[4:5], v[58:59], v[36:37], v[60:61] op_sel_hi:[0,1,1]
	v_pk_fma_f32 v[6:7], v[58:59], v[38:39], v[62:63] op_sel_hi:[0,1,1]
	ds_read_b128 v[36:39], v76 offset:31488
	s_waitcnt lgkmcnt(6)
	v_pk_mul_f32 v[56:57], v[4:5], v[12:13]
	v_pk_mul_f32 v[64:65], v[4:5], v[40:41]
	v_pk_fma_f32 v[56:57], v[6:7], v[14:15], v[56:57]
	ds_read_b128 v[12:15], v76 offset:27648
	v_pk_fma_f32 v[64:65], v[6:7], v[42:43], v[64:65]
	ds_read_b128 v[40:43], v76 offset:35584
	v_add_f32_e32 v58, v56, v57
	v_pk_mul_f32 v[60:61], v[54:55], v[24:25] op_sel_hi:[0,1]
	v_pk_mul_f32 v[62:63], v[54:55], v[26:27] op_sel_hi:[0,1]
	v_add_f32_dpp v58, v58, v58 quad_perm:[1,0,3,2] row_mask:0xf bank_mask:0xf bound_ctrl:1
	ds_read_b128 v[24:27], v76 offset:39936
	v_add_f32_e32 v67, v64, v65
	v_add_f32_dpp v58, v58, v58 quad_perm:[2,3,0,1] row_mask:0xf bank_mask:0xf bound_ctrl:1
	v_pk_fma_f32 v[60:61], v[4:5], v[8:9], v[60:61]
	v_pk_fma_f32 v[62:63], v[6:7], v[10:11], v[62:63]
	v_add_f32_dpp v70, v66, v66 row_mirror row_mask:0xf bank_mask:0x3
	v_add_f32_dpp v58, v58, v58 row_half_mirror row_mask:0xf bank_mask:0xf bound_ctrl:1
	ds_read_b128 v[8:11], v76 offset:23552
	v_add_f32_dpp v70, v67, v67 row_mirror row_mask:0xf bank_mask:0xc
	v_add_f32_dpp v58, v58, v58 row_mirror row_mask:0xf bank_mask:0xf bound_ctrl:1
	v_pk_fma_f32 v[4:5], v[58:59], v[16:17], v[60:61] op_sel_hi:[0,1,1]
	v_pk_fma_f32 v[6:7], v[58:59], v[18:19], v[62:63] op_sel_hi:[0,1,1]
	ds_read_b128 v[16:19], v76 offset:31744
	s_waitcnt lgkmcnt(5)
	v_pk_mul_f32 v[56:57], v[4:5], v[32:33]
	v_pk_mul_f32 v[64:65], v[4:5], v[20:21]
	v_pk_fma_f32 v[56:57], v[6:7], v[34:35], v[56:57]
	ds_read_b128 v[32:35], v76 offset:27904
	v_pk_fma_f32 v[64:65], v[6:7], v[22:23], v[64:65]
	ds_read_b128 v[20:23], v76 offset:35840
	v_add_f32_e32 v58, v56, v57
	v_pk_mul_f32 v[60:61], v[54:55], v[44:45] op_sel:[1,0] op_sel_hi:[1,1]
	v_pk_mul_f32 v[62:63], v[54:55], v[46:47] op_sel:[1,0] op_sel_hi:[1,1]
	v_add_f32_dpp v58, v58, v58 quad_perm:[1,0,3,2] row_mask:0xf bank_mask:0xf bound_ctrl:1
	ds_read_b128 v[44:47], v76 offset:40192
	v_add_f32_e32 v66, v64, v65
	v_add_f32_dpp v58, v58, v58 quad_perm:[2,3,0,1] row_mask:0xf bank_mask:0xf bound_ctrl:1
	v_pk_fma_f32 v[60:61], v[4:5], v[28:29], v[60:61]
	v_pk_fma_f32 v[62:63], v[6:7], v[30:31], v[62:63]
	v_add_f32_dpp v58, v58, v58 row_half_mirror row_mask:0xf bank_mask:0xf bound_ctrl:1
	ds_read_b128 v[28:31], v76 offset:23808
	s_nop 0
	v_add_f32_dpp v58, v58, v58 row_mirror row_mask:0xf bank_mask:0xf bound_ctrl:1
	v_pk_fma_f32 v[4:5], v[58:59], v[36:37], v[60:61] op_sel_hi:[0,1,1]
	v_pk_fma_f32 v[6:7], v[58:59], v[38:39], v[62:63] op_sel_hi:[0,1,1]
	ds_read_b128 v[36:39], v76 offset:32000
	s_waitcnt lgkmcnt(5)
; DI void scan_task(const Params& p, int l, int isP, int b, int h, int rg, char* smem, const bool dry) {
;     ...
; #pragma unroll
;     for (int s = 0; s < 32; s++) {
;       f32x4 w4n = w4, a4n = a4, b4n = b4;
;       uint2 urn = ur, ukn = uk;
;       float vn = v;
;       if (s < 31) {
;         w4n = *(const f32x4*)(fw + (s + 1) * 64);
;         a4n = *(const f32x4*)(fa + (s + 1) * 64);
;         b4n = *(const f32x4*)(fb + (s + 1) * 64);
;         urn = *(const uint2*)(pr + (s + 1) * 128);
;         ukn = *(const uint2*)(pk + (s + 1) * 128);
;         vn = vb[(s + 1) * 16];
;       }
;       __builtin_amdgcn_sched_barrier(0);
;       const f32x2 klo = {__uint_as_float(uk.x << 16), __uint_as_float(uk.x & 0xFFFF0000u)};
;       const f32x2 khi = {__uint_as_float(uk.y << 16), __uint_as_float(uk.y & 0xFFFF0000u)};
;       const f32x2 rlo = {__uint_as_float(ur.x << 16), __uint_as_float(ur.x & 0xFFFF0000u)};
;       const f32x2 rhi = {__uint_as_float(ur.y << 16), __uint_as_float(ur.y & 0xFFFF0000u)};
;       const f32x2 vv = {v, v};
;       const f32x2 t = Sa * a4.lo + Sb * a4.hi;
;       const f32x2 na = Sa * w4.lo + vv * klo;
;       const f32x2 nb = Sb * w4.hi + vv * khi;
;       float sa = t.x + t.y;
;       float yp = yprev;
;       rowsum16x2(sa, yp);
;       if (s >= 1 && s <= 16) ykeep0 = (jq == s - 1) ? yp : ykeep0;
;       if (s >= 17) ykeep1 = (jq == s - 17) ? yp : ykeep1;
;       const f32x2 sv = {sa, sa};
;       Sa = na + sv * b4.lo;
;       Sb = nb + sv * b4.hi;
;       const f32x2 yy = Sa * rlo + Sb * rhi;
;       yprev = yy.x + yy.y;
;       w4 = w4n; a4 = a4n; b4 = b4n; ur = urn; uk = ukn; v = vn;
;     }
	v_pk_mul_f32 v[56:57], v[4:5], v[12:13]
	v_pk_mul_f32 v[64:65], v[4:5], v[40:41]
	v_pk_fma_f32 v[56:57], v[6:7], v[14:15], v[56:57]
	ds_read_b128 v[12:15], v76 offset:28160
	v_pk_fma_f32 v[64:65], v[6:7], v[42:43], v[64:65]
	ds_read_b128 v[40:43], v76 offset:36096
	v_add_f32_e32 v58, v56, v57
	v_pk_mul_f32 v[60:61], v[48:49], v[24:25] op_sel_hi:[0,1]
	v_pk_mul_f32 v[62:63], v[48:49], v[26:27] op_sel_hi:[0,1]
	v_add_f32_dpp v58, v58, v58 quad_perm:[1,0,3,2] row_mask:0xf bank_mask:0xf bound_ctrl:1
	ds_read_b128 v[24:27], v76 offset:40448
	v_add_f32_e32 v67, v64, v65
	v_add_f32_dpp v58, v58, v58 quad_perm:[2,3,0,1] row_mask:0xf bank_mask:0xf bound_ctrl:1
	v_pk_fma_f32 v[60:61], v[4:5], v[8:9], v[60:61]
	v_pk_fma_f32 v[62:63], v[6:7], v[10:11], v[62:63]
	v_add_f32_dpp v71, v66, v66 row_mirror row_mask:0xf bank_mask:0x3
	v_add_f32_dpp v58, v58, v58 row_half_mirror row_mask:0xf bank_mask:0xf bound_ctrl:1
	ds_read_b128 v[8:11], v76 offset:24064
	v_add_f32_dpp v71, v67, v67 row_mirror row_mask:0xf bank_mask:0xc
	v_add_f32_dpp v58, v58, v58 row_mirror row_mask:0xf bank_mask:0xf bound_ctrl:1
	v_pk_fma_f32 v[4:5], v[58:59], v[16:17], v[60:61] op_sel_hi:[0,1,1]
	v_pk_fma_f32 v[6:7], v[58:59], v[18:19], v[62:63] op_sel_hi:[0,1,1]
	ds_read_b128 v[16:19], v76 offset:32256
	s_waitcnt lgkmcnt(5)
	v_pk_mul_f32 v[56:57], v[4:5], v[32:33]
	v_pk_mul_f32 v[64:65], v[4:5], v[20:21]
	v_pk_fma_f32 v[56:57], v[6:7], v[34:35], v[56:57]
	ds_read_b128 v[32:35], v76 offset:28416
	v_pk_fma_f32 v[64:65], v[6:7], v[22:23], v[64:65]
	ds_read_b128 v[20:23], v76 offset:36352
	v_add_f32_e32 v58, v56, v57
	v_pk_mul_f32 v[60:61], v[48:49], v[44:45] op_sel:[1,0] op_sel_hi:[1,1]
	v_pk_mul_f32 v[62:63], v[48:49], v[46:47] op_sel:[1,0] op_sel_hi:[1,1]
	v_add_f32_dpp v58, v58, v58 quad_perm:[1,0,3,2] row_mask:0xf bank_mask:0xf bound_ctrl:1
	ds_read_b128 v[44:47], v76 offset:40704
	v_add_f32_e32 v66, v64, v65
	ds_read_b128 v[52:55], v77 offset:42032
	v_add_f32_dpp v58, v58, v58 quad_perm:[2,3,0,1] row_mask:0xf bank_mask:0xf bound_ctrl:1
	v_pk_fma_f32 v[60:61], v[4:5], v[28:29], v[60:61]
	v_pk_fma_f32 v[62:63], v[6:7], v[30:31], v[62:63]
	v_add_f32_dpp v70, v70, v70 row_half_mirror row_mask:0xf bank_mask:0x5
	v_add_f32_dpp v58, v58, v58 row_half_mirror row_mask:0xf bank_mask:0xf bound_ctrl:1
	ds_read_b128 v[28:31], v76 offset:24320
	v_add_f32_dpp v70, v71, v71 row_half_mirror row_mask:0xf bank_mask:0xa
	v_add_f32_dpp v58, v58, v58 row_mirror row_mask:0xf bank_mask:0xf bound_ctrl:1
	v_pk_fma_f32 v[4:5], v[58:59], v[36:37], v[60:61] op_sel_hi:[0,1,1]
	v_pk_fma_f32 v[6:7], v[58:59], v[38:39], v[62:63] op_sel_hi:[0,1,1]
	ds_read_b128 v[36:39], v76 offset:32512
	s_waitcnt lgkmcnt(6)
	v_pk_mul_f32 v[56:57], v[4:5], v[12:13]
	v_pk_mul_f32 v[64:65], v[4:5], v[40:41]
	v_pk_fma_f32 v[56:57], v[6:7], v[14:15], v[56:57]
	ds_read_b128 v[12:15], v76 offset:28672
	v_pk_fma_f32 v[64:65], v[6:7], v[42:43], v[64:65]
	ds_read_b128 v[40:43], v76 offset:36608
	v_add_f32_e32 v58, v56, v57
	v_pk_mul_f32 v[60:61], v[50:51], v[24:25] op_sel_hi:[0,1]
	v_pk_mul_f32 v[62:63], v[50:51], v[26:27] op_sel_hi:[0,1]
	v_add_f32_dpp v58, v58, v58 quad_perm:[1,0,3,2] row_mask:0xf bank_mask:0xf bound_ctrl:1
	ds_read_b128 v[24:27], v76 offset:40960
	v_add_f32_e32 v67, v64, v65
	v_add_f32_dpp v58, v58, v58 quad_perm:[2,3,0,1] row_mask:0xf bank_mask:0xf bound_ctrl:1
	v_pk_fma_f32 v[60:61], v[4:5], v[8:9], v[60:61]
	v_pk_fma_f32 v[62:63], v[6:7], v[10:11], v[62:63]
	v_add_f32_dpp v72, v66, v66 row_mirror row_mask:0xf bank_mask:0x3
	v_add_f32_dpp v58, v58, v58 row_half_mirror row_mask:0xf bank_mask:0xf bound_ctrl:1
	ds_read_b128 v[8:11], v76 offset:24576
	v_add_f32_dpp v72, v67, v67 row_mirror row_mask:0xf bank_mask:0xc
	v_add_f32_dpp v58, v58, v58 row_mirror row_mask:0xf bank_mask:0xf bound_ctrl:1
	v_pk_fma_f32 v[4:5], v[58:59], v[16:17], v[60:61] op_sel_hi:[0,1,1]
	v_pk_fma_f32 v[6:7], v[58:59], v[18:19], v[62:63] op_sel_hi:[0,1,1]
	ds_read_b128 v[16:19], v76 offset:32768
	s_waitcnt lgkmcnt(5)
	v_pk_mul_f32 v[56:57], v[4:5], v[32:33]
	v_pk_mul_f32 v[64:65], v[4:5], v[20:21]
	v_pk_fma_f32 v[56:57], v[6:7], v[34:35], v[56:57]
	ds_read_b128 v[32:35], v76 offset:28928
	v_pk_fma_f32 v[64:65], v[6:7], v[22:23], v[64:65]
	ds_read_b128 v[20:23], v76 offset:36864
	v_add_f32_e32 v58, v56, v57
	v_pk_mul_f32 v[60:61], v[50:51], v[44:45] op_sel:[1,0] op_sel_hi:[1,1]
	v_pk_mul_f32 v[62:63], v[50:51], v[46:47] op_sel:[1,0] op_sel_hi:[1,1]
	v_add_f32_dpp v58, v58, v58 quad_perm:[1,0,3,2] row_mask:0xf bank_mask:0xf bound_ctrl:1
	ds_read_b128 v[44:47], v76 offset:41216
	v_add_f32_e32 v66, v64, v65
	v_add_f32_dpp v58, v58, v58 quad_perm:[2,3,0,1] row_mask:0xf bank_mask:0xf bound_ctrl:1
	v_pk_fma_f32 v[60:61], v[4:5], v[28:29], v[60:61]
	v_pk_fma_f32 v[62:63], v[6:7], v[30:31], v[62:63]
	v_add_f32_dpp v58, v58, v58 row_half_mirror row_mask:0xf bank_mask:0xf bound_ctrl:1
	ds_read_b128 v[28:31], v76 offset:24832
	s_nop 0
	v_add_f32_dpp v58, v58, v58 row_mirror row_mask:0xf bank_mask:0xf bound_ctrl:1
	v_pk_fma_f32 v[4:5], v[58:59], v[36:37], v[60:61] op_sel_hi:[0,1,1]
	v_pk_fma_f32 v[6:7], v[58:59], v[38:39], v[62:63] op_sel_hi:[0,1,1]
	ds_read_b128 v[36:39], v76 offset:33024
	s_waitcnt lgkmcnt(5)
; DI void scan_task(const Params& p, int l, int isP, int b, int h, int rg, char* smem, const bool dry) {
;     ...
;   auto sstore = [&](int bi) {
;     char* bb = smem + bi * BUFB;
;     *(float4*)(bb + (ds * 64 + dj * 4) * 4) = rd0;
;     *(float4*)(bb + ((16 + ds) * 64 + dj * 4) * 4) = rd1;
;     {
;       CVT8(qa, alo, ahi)
;       float* d = (float*)(bb + 8192) + lst * 64 + lch * 8;
;       *(float4*)d = alo; *(float4*)(d + 4) = ahi;
;     }
;     {
;       CVT8(qb, blo, bhi)
;       float* d = (float*)(bb + 16384) + lst * 64 + lch * 8;
;       *(float4*)d = blo; *(float4*)(d + 4) = bhi;
;     }
;     *(uint4*)(bb + 24576 + (lst * 64 + lch * 8) * 2) = qr;
;     *(uint4*)(bb + 28672 + (lst * 64 + lch * 8) * 2) = qk;
;     if (tid < 64) {
;       const int s = tid >> 1, half = tid & 1;
;       CVT8(rv, vlo, vhi)
;       float* d = (float*)(bb + 32768) + s * 16 + half * 8;
;       *(float4*)d = vlo; *(float4*)(d + 4) = vhi;
;     }
;   };
;     ...
;       const f32x2 t = Sa * a4.lo + Sb * a4.hi;
;       const f32x2 na = Sa * w4.lo + vv * klo;
;       const f32x2 nb = Sb * w4.hi + vv * khi;
;       float sa = t.x + t.y;
;       float yp = yprev;
;       rowsum16x2(sa, yp);
;       if (s >= 1 && s <= 16) ykeep0 = (jq == s - 1) ? yp : ykeep0;
;       if (s >= 17) ykeep1 = (jq == s - 17) ? yp : ykeep1;
;       const f32x2 sv = {sa, sa};
;       Sa = na + sv * b4.lo;
;       Sb = nb + sv * b4.hi;
;       const f32x2 yy = Sa * rlo + Sb * rhi;
;       yprev = yy.x + yy.y;
;       w4 = w4n; a4 = a4n; b4 = b4n; ur = urn; uk = ukn; v = vn;
;     }
;     {
;       const float yl = rowsum16(yprev);
;       ykeep1 = (jq == 15) ? yl : ykeep1;
;     }
;     if (!dry) { yo[0] = ykeep0; yo[(size_t)16 * 512] = ykeep1; }
;     if (more) sstore((c + 1) & 1);
;     __syncthreads();
	v_pk_mul_f32 v[56:57], v[4:5], v[12:13]
	v_pk_mul_f32 v[64:65], v[4:5], v[40:41]
	v_pk_fma_f32 v[56:57], v[6:7], v[14:15], v[56:57]
	ds_read_b128 v[12:15], v76 offset:29184
	v_pk_fma_f32 v[64:65], v[6:7], v[42:43], v[64:65]
	ds_read_b128 v[40:43], v76 offset:37120
	v_add_f32_e32 v58, v56, v57
	v_pk_mul_f32 v[60:61], v[52:53], v[24:25] op_sel_hi:[0,1]
	v_pk_mul_f32 v[62:63], v[52:53], v[26:27] op_sel_hi:[0,1]
	v_add_f32_dpp v58, v58, v58 quad_perm:[1,0,3,2] row_mask:0xf bank_mask:0xf bound_ctrl:1
	ds_read_b128 v[24:27], v76 offset:41472
	v_add_f32_e32 v67, v64, v65
	v_add_f32_dpp v58, v58, v58 quad_perm:[2,3,0,1] row_mask:0xf bank_mask:0xf bound_ctrl:1
	v_pk_fma_f32 v[60:61], v[4:5], v[8:9], v[60:61]
	v_pk_fma_f32 v[62:63], v[6:7], v[10:11], v[62:63]
	v_add_f32_dpp v73, v66, v66 row_mirror row_mask:0xf bank_mask:0x3
	v_add_f32_dpp v58, v58, v58 row_half_mirror row_mask:0xf bank_mask:0xf bound_ctrl:1
	ds_read_b128 v[8:11], v76 offset:25088
	v_add_f32_dpp v73, v67, v67 row_mirror row_mask:0xf bank_mask:0xc
	v_add_f32_dpp v58, v58, v58 row_mirror row_mask:0xf bank_mask:0xf bound_ctrl:1
	v_pk_fma_f32 v[4:5], v[58:59], v[16:17], v[60:61] op_sel_hi:[0,1,1]
	v_pk_fma_f32 v[6:7], v[58:59], v[18:19], v[62:63] op_sel_hi:[0,1,1]
	ds_read_b128 v[16:19], v76 offset:33280
	s_waitcnt lgkmcnt(5)
	v_pk_mul_f32 v[56:57], v[4:5], v[32:33]
	v_pk_mul_f32 v[64:65], v[4:5], v[20:21]
	v_pk_fma_f32 v[56:57], v[6:7], v[34:35], v[56:57]
	ds_read_b128 v[32:35], v76 offset:29440
	v_pk_fma_f32 v[64:65], v[6:7], v[22:23], v[64:65]
	ds_read_b128 v[20:23], v76 offset:37376
	v_add_f32_e32 v58, v56, v57
	v_pk_mul_f32 v[60:61], v[52:53], v[44:45] op_sel:[1,0] op_sel_hi:[1,1]
	v_pk_mul_f32 v[62:63], v[52:53], v[46:47] op_sel:[1,0] op_sel_hi:[1,1]
	v_add_f32_dpp v58, v58, v58 quad_perm:[1,0,3,2] row_mask:0xf bank_mask:0xf bound_ctrl:1
	ds_read_b128 v[44:47], v76 offset:41728
	v_add_f32_e32 v66, v64, v65
	v_add_f32_dpp v58, v58, v58 quad_perm:[2,3,0,1] row_mask:0xf bank_mask:0xf bound_ctrl:1
	v_pk_fma_f32 v[60:61], v[4:5], v[28:29], v[60:61]
	v_pk_fma_f32 v[62:63], v[6:7], v[30:31], v[62:63]
	v_add_f32_dpp v72, v72, v72 row_half_mirror row_mask:0xf bank_mask:0x5
	v_add_f32_dpp v58, v58, v58 row_half_mirror row_mask:0xf bank_mask:0xf bound_ctrl:1
	ds_read_b128 v[28:31], v76 offset:25344
	v_add_f32_dpp v72, v73, v73 row_half_mirror row_mask:0xf bank_mask:0xa
	v_add_f32_dpp v58, v58, v58 row_mirror row_mask:0xf bank_mask:0xf bound_ctrl:1
	v_pk_fma_f32 v[4:5], v[58:59], v[36:37], v[60:61] op_sel_hi:[0,1,1]
	v_pk_fma_f32 v[6:7], v[58:59], v[38:39], v[62:63] op_sel_hi:[0,1,1]
	ds_read_b128 v[36:39], v76 offset:33536
	s_waitcnt lgkmcnt(5)
	v_pk_mul_f32 v[56:57], v[4:5], v[12:13]
	v_pk_mul_f32 v[64:65], v[4:5], v[40:41]
	v_pk_fma_f32 v[56:57], v[6:7], v[14:15], v[56:57]
	v_pk_fma_f32 v[64:65], v[6:7], v[42:43], v[64:65]
	ds_read_b128 v[40:43], v76 offset:37632
	v_add_f32_e32 v58, v56, v57
	v_pk_mul_f32 v[60:61], v[54:55], v[24:25] op_sel_hi:[0,1]
	v_pk_mul_f32 v[62:63], v[54:55], v[26:27] op_sel_hi:[0,1]
	v_add_f32_dpp v58, v58, v58 quad_perm:[1,0,3,2] row_mask:0xf bank_mask:0xf bound_ctrl:1
	v_add_f32_e32 v67, v64, v65
	s_nop 0
	v_add_f32_dpp v58, v58, v58 quad_perm:[2,3,0,1] row_mask:0xf bank_mask:0xf bound_ctrl:1
	v_pk_fma_f32 v[60:61], v[4:5], v[8:9], v[60:61]
	v_pk_fma_f32 v[62:63], v[6:7], v[10:11], v[62:63]
	v_add_f32_dpp v74, v66, v66 row_mirror row_mask:0xf bank_mask:0x3
	v_add_f32_dpp v58, v58, v58 row_half_mirror row_mask:0xf bank_mask:0xf bound_ctrl:1
	s_nop 0
	v_add_f32_dpp v74, v67, v67 row_mirror row_mask:0xf bank_mask:0xc
	v_add_f32_dpp v58, v58, v58 row_mirror row_mask:0xf bank_mask:0xf bound_ctrl:1
	v_pk_fma_f32 v[4:5], v[58:59], v[16:17], v[60:61] op_sel_hi:[0,1,1]
	v_pk_fma_f32 v[6:7], v[58:59], v[18:19], v[62:63] op_sel_hi:[0,1,1]
	s_waitcnt lgkmcnt(1)
	v_pk_mul_f32 v[56:57], v[4:5], v[32:33]
	v_pk_mul_f32 v[64:65], v[4:5], v[20:21]
	v_pk_fma_f32 v[56:57], v[6:7], v[34:35], v[56:57]
	v_pk_fma_f32 v[64:65], v[6:7], v[22:23], v[64:65]
	v_add_f32_e32 v58, v56, v57
	v_pk_mul_f32 v[60:61], v[54:55], v[44:45] op_sel:[1,0] op_sel_hi:[1,1]
	v_pk_mul_f32 v[62:63], v[54:55], v[46:47] op_sel:[1,0] op_sel_hi:[1,1]
	v_add_f32_dpp v58, v58, v58 quad_perm:[1,0,3,2] row_mask:0xf bank_mask:0xf bound_ctrl:1
	v_add_f32_e32 v66, v64, v65
	s_nop 0
	v_add_f32_dpp v58, v58, v58 quad_perm:[2,3,0,1] row_mask:0xf bank_mask:0xf bound_ctrl:1
	v_pk_fma_f32 v[60:61], v[4:5], v[28:29], v[60:61]
	v_pk_fma_f32 v[62:63], v[6:7], v[30:31], v[62:63]
	v_add_f32_dpp v58, v58, v58 row_half_mirror row_mask:0xf bank_mask:0xf bound_ctrl:1
	s_nop 1
	v_add_f32_dpp v58, v58, v58 row_mirror row_mask:0xf bank_mask:0xf bound_ctrl:1
	v_pk_fma_f32 v[4:5], v[58:59], v[36:37], v[60:61] op_sel_hi:[0,1,1]
	v_pk_fma_f32 v[6:7], v[58:59], v[38:39], v[62:63] op_sel_hi:[0,1,1]
	s_waitcnt lgkmcnt(0)
	v_pk_mul_f32 v[64:65], v[4:5], v[40:41]
	v_pk_fma_f32 v[64:65], v[6:7], v[42:43], v[64:65]
	v_add_f32_e32 v67, v64, v65
	s_cmp_lg_u32 s22, 0
	s_cbranch_scc0 .Lscan_lastB
	s_waitcnt vmcnt(6)
	ds_write_b128 v78, v[84:87] offset:0
	v_lshlrev_b32_e32 v8, 16, v92
	v_and_b32_e32 v9, 0xffff0000, v92
	v_lshlrev_b32_e32 v10, 16, v93
	v_and_b32_e32 v11, 0xffff0000, v93
	ds_write_b128 v78, v[8:11] offset:4096
	v_lshlrev_b32_e32 v12, 16, v94
	v_and_b32_e32 v13, 0xffff0000, v94
	v_lshlrev_b32_e32 v14, 16, v95
	v_and_b32_e32 v15, 0xffff0000, v95
	ds_write_b128 v78, v[12:15] offset:8192
	v_lshlrev_b32_e32 v16, 16, v88
	v_and_b32_e32 v17, 0xffff0000, v88
	v_lshlrev_b32_e32 v18, 16, v89
	v_and_b32_e32 v19, 0xffff0000, v89
	ds_write_b128 v78, v[16:19] offset:12288
	v_lshlrev_b32_e32 v20, 16, v90
	v_and_b32_e32 v21, 0xffff0000, v90
	v_lshlrev_b32_e32 v22, 16, v91
	v_and_b32_e32 v23, 0xffff0000, v91
	ds_write_b128 v78, v[20:23] offset:16384
	v_lshlrev_b32_e32 v24, 16, v96
	ds_write_b32 v79, v24 offset:20480
	s_waitcnt lgkmcnt(0)
	s_barrier
	ds_read_b128 v[12:15], v76 offset:4096
	ds_read_b128 v[24:27], v76 offset:16384
	ds_read_b128 v[48:51], v77 offset:20480
	ds_read_b128 v[8:11], v76 offset:0
	ds_read_b128 v[16:19], v76 offset:8192
	ds_read_b128 v[20:23], v76 offset:12288
	ds_read_b128 v[32:35], v76 offset:4352
	ds_read_b128 v[44:47], v76 offset:16640
	ds_read_b128 v[28:31], v76 offset:256
	ds_read_b128 v[36:39], v76 offset:8448
	ds_read_b128 v[40:43], v76 offset:12544
	s_branch .Lscan_tailB

; DI void scan_task(const Params& p, int l, int isP, int b, int h, int rg, char* smem, const bool dry) {
;     ...
;     {
;       const float yl = rowsum16(yprev);
;       ykeep1 = (jq == 15) ? yl : ykeep1;
;     }
;     if (!dry) { yo[0] = ykeep0; yo[(size_t)16 * 512] = ykeep1; }
;     if (more) sstore((c + 1) & 1);
;     __syncthreads();
;   }
;   float* so = isP ? p.out + O_WKVP + ((size_t)((l * 2 + b) * 8 + h) * 64 + i) * 64 + jq * 4
;                   : p.out + O_WKVS + ((size_t)((l * 32 + b) * 8 + h) * 64 + i) * 64 + jq * 4;
;   if (!dry) *(float4*)so = make_float4(Sa.x, Sa.y, Sb.x, Sb.y);
;   __builtin_amdgcn_s_setprio(0);
.Lscan_tailB:
	v_add_f32_dpp v75, v66, v66 row_mirror row_mask:0xf bank_mask:0x3
	v_add_f32_dpp v74, v74, v74 row_half_mirror row_mask:0xf bank_mask:0x5
	v_add_f32_dpp v68, v68, v68 quad_perm:[1,0,3,2] row_mask:0xf bank_mask:0xf
	v_add_f32_dpp v75, v67, v67 row_mirror row_mask:0xf bank_mask:0xc
	v_add_f32_dpp v70, v70, v70 quad_perm:[1,0,3,2] row_mask:0xf bank_mask:0xf
	v_add_f32_dpp v72, v72, v72 quad_perm:[1,0,3,2] row_mask:0xf bank_mask:0xf
	v_add_f32_dpp v74, v75, v75 row_half_mirror row_mask:0xf bank_mask:0xa
	v_add_f32_dpp v68, v68, v68 quad_perm:[2,3,0,1] row_mask:0xf bank_mask:0xf
	v_add_f32_dpp v70, v70, v70 quad_perm:[2,3,0,1] row_mask:0xf bank_mask:0xf
	v_add_f32_dpp v74, v74, v74 quad_perm:[1,0,3,2] row_mask:0xf bank_mask:0xf
	v_add_f32_dpp v72, v72, v72 quad_perm:[2,3,0,1] row_mask:0xf bank_mask:0xf
	v_cndmask_b32_e64 v68, v68, v70, s[18:19]
	v_add_f32_dpp v74, v74, v74 quad_perm:[2,3,0,1] row_mask:0xf bank_mask:0xf
	v_cndmask_b32_e64 v72, v72, v74, s[18:19]
	v_cndmask_b32_e64 v68, v68, v72, s[20:21]
	global_store_dword v83, v68, s[14:15]
	s_add_u32 s14, s14, 0x8000
	s_addc_u32 s15, s15, 0
	s_add_i32 s16, s16, 2
	s_cmp_lt_u32 s16, s17
	s_cbranch_scc1 .Lscan_loop
	s_waitcnt vmcnt(0)
	global_store_dwordx4 v59, v[4:7], s[24:25]
	v_readlane_b32 s10, v254, 51
	v_readlane_b32 s11, v254, 52
	s_setprio 0
	v_readlane_b32 s26, v254, 59
	v_readlane_b32 s27, v254, 60
